# hgrn_pre: counted vmcnt instead of draining stores; spatial: LN gain/bias loads first + counted waits; residual GEMM epilogue: merged operand/residual load waits, counted waits leave next-group loads
# speedup vs baseline: 1.0364x; 1.0094x over previous
.LBB0_292:
	v_lshl_add_u64 v[234:235], v[84:85], 0, s[28:29]
	v_lshl_add_u64 v[236:237], v[86:87], 0, s[28:29]
	global_load_dwordx2 v[230:231], v[234:235], off
	global_load_dwordx2 v[232:233], v[236:237], off
	v_lshl_add_u64 v[114:115], v[90:91], 0, s[36:37]
	s_mov_b32 s20, 0xc914000
	v_add_co_u32_e32 v2, vcc, s20, v114
	global_load_dwordx4 v[36:39], v[82:83], off offset:-240
	global_load_dwordx4 v[44:47], v[82:83], off offset:-256
	global_load_dwordx4 v[20:23], v[82:83], off offset:-112
	global_load_dwordx4 v[24:27], v[82:83], off offset:-128
	global_load_dwordx4 v[12:15], v[82:83], off offset:16
	global_load_dwordx4 v[16:19], v[82:83], off
	global_load_dwordx4 v[4:7], v[82:83], off offset:144
	global_load_dwordx4 v[8:11], v[82:83], off offset:128
	v_addc_co_u32_e32 v3, vcc, 0, v115, vcc
	global_load_dwordx2 v[118:119], v[2:3], off
	global_load_dwordx2 v[116:117], v[2:3], off offset:32
	global_load_dwordx2 v[112:113], v[2:3], off offset:64
	global_load_dwordx2 v[110:111], v[2:3], off offset:96
	global_load_dwordx2 v[108:109], v[2:3], off offset:128
	global_load_dwordx2 v[106:107], v[2:3], off offset:160
	global_load_dwordx2 v[104:105], v[2:3], off offset:192
	global_load_dwordx2 v[102:103], v[2:3], off offset:224
	v_lshl_add_u64 v[2:3], v[88:89], 0, s[28:29]
	global_load_dword v100, v[2:3], off
	s_cmpk_eq_i32 s36, 0x300
	s_cbranch_scc1 .Lsp_lastg
	v_lshl_add_u64 v[2:3], v[92:93], 0, s[36:37]
	v_add_co_u32_e32 v40, vcc, 0xe954000, v2
	s_mov_b32 s20, 0xe954000
	s_nop 0
	v_addc_co_u32_e32 v41, vcc, 0, v3, vcc
	global_load_dword v125, v[40:41], off offset:256
	global_load_dword v126, v[40:41], off offset:2304
	v_add_co_u32_e32 v40, vcc, 0xe955000, v2
	s_nop 1
	v_addc_co_u32_e32 v41, vcc, 0, v3, vcc
	global_load_dword v127, v[40:41], off offset:256
	global_load_dword v128, v[40:41], off offset:2304
	v_add_co_u32_e32 v40, vcc, 0xe956000, v2
	s_nop 1
	v_addc_co_u32_e32 v41, vcc, 0, v3, vcc
	v_add_co_u32_e32 v2, vcc, 0xe957000, v2
	global_load_dword v129, v[40:41], off offset:256
	global_load_dword v130, v[40:41], off offset:2304
	v_addc_co_u32_e32 v3, vcc, 0, v3, vcc
	global_load_dword v131, v[2:3], off offset:256
	global_load_dword v132, v[2:3], off offset:2304
	v_lshl_add_u64 v[2:3], v[94:95], 0, s[36:37]
	v_add_co_u32_e32 v40, vcc, s20, v2
	s_nop 1
	v_addc_co_u32_e32 v41, vcc, 0, v3, vcc
	global_load_dword v133, v[40:41], off offset:256
	global_load_dword v134, v[40:41], off offset:2304
	v_add_co_u32_e32 v40, vcc, 0xe955000, v2
	s_nop 1
	v_addc_co_u32_e32 v41, vcc, 0, v3, vcc
	global_load_dword v135, v[40:41], off offset:256
	global_load_dword v136, v[40:41], off offset:2304
	v_add_co_u32_e32 v40, vcc, 0xe956000, v2
	s_nop 1
	v_addc_co_u32_e32 v41, vcc, 0, v3, vcc
	v_add_co_u32_e32 v2, vcc, 0xe957000, v2
	global_load_dword v137, v[40:41], off offset:256
	global_load_dword v138, v[40:41], off offset:2304
	v_addc_co_u32_e32 v3, vcc, 0, v3, vcc
	global_load_dword v139, v[2:3], off offset:256
	global_load_dword v140, v[2:3], off offset:2304
	s_waitcnt vmcnt(33)
	s_branch .LBB0_294
.Lsp_lastg:
	s_waitcnt vmcnt(17)
.LBB0_294:
	v_mov_b32_e32 v2, v230
	v_mov_b32_e32 v3, v231
	v_mov_b32_e32 v40, v232
	v_mov_b32_e32 v41, v233
	ds_read_b64 v[42:43], v123 offset:34816
	v_lshlrev_b32_e32 v60, 16, v28
	v_and_b32_e32 v61, 0xffff0000, v28
	v_cndmask_b32_e64 v28, 0, 1, s[40:41]
	v_cmp_ne_u32_e64 s[20:21], 1, v28
	s_waitcnt lgkmcnt(0)
	v_pk_add_f32 v[28:29], v[60:61], v[42:43] op_sel_hi:[1,0] neg_lo:[0,1] neg_hi:[0,1]
	s_andn2_b64 vcc, exec, s[40:41]
	v_pk_mul_f32 v[28:29], v[42:43], v[28:29] op_sel:[1,0]
	v_lshl_add_u64 v[42:43], v[96:97], 0, s[28:29]
	v_pk_fma_f32 v[28:29], v[2:3], v[28:29], v[40:41]
	s_cbranch_vccnz .LBB0_296
	v_add_co_u32_e32 v60, vcc, 0xc880000, v42
	s_nop 1
	v_addc_co_u32_e32 v61, vcc, 0, v43, vcc
	global_store_dwordx2 v[60:61], v[28:29], off

.LBB0_326:
	v_cvt_pk_bf16_f32 v35, v48, v2
	v_cvt_pk_bf16_f32 v31, v49, v3
	ds_write_b128 v122, v[32:35] offset:128
	ds_write_b128 v122, v[28:31] offset:400
	s_waitcnt lgkmcnt(0)
	s_barrier
	s_waitcnt vmcnt(0)
	v_mov_b32_e32 v2, v0
	v_mov_b32_e32 v3, v0
	v_mov_b32_e32 v1, v0
	v_mov_b64_e32 v[30:31], v[2:3]
	v_mov_b64_e32 v[34:35], v[2:3]
	v_mov_b64_e32 v[42:43], v[2:3]
	v_mov_b64_e32 v[50:51], v[2:3]
	v_mov_b64_e32 v[54:55], v[2:3]
	v_mov_b64_e32 v[58:59], v[2:3]
	v_mov_b64_e32 v[62:63], v[2:3]
	v_mov_b64_e32 v[66:67], v[2:3]
	v_mov_b64_e32 v[28:29], v[0:1]
	v_mov_b64_e32 v[32:33], v[0:1]
	v_mov_b64_e32 v[40:41], v[0:1]
	v_mov_b64_e32 v[48:49], v[0:1]
	v_mov_b64_e32 v[52:53], v[0:1]
	v_mov_b64_e32 v[56:57], v[0:1]
	v_mov_b64_e32 v[60:61], v[0:1]
	v_mov_b64_e32 v[64:65], v[0:1]
	s_and_saveexec_b64 s[20:21], s[42:43]
	s_cbranch_execz .LBB0_330
	v_cndmask_b32_e64 v1, v44, 0, s[46:47]
	v_cndmask_b32_e64 v3, v46, 0, s[50:51]
	v_cndmask_b32_e64 v28, v47, 0, s[48:49]
	v_cndmask_b32_e64 v29, v36, 0, s[54:55]
	v_cndmask_b32_e64 v33, v38, 0, s[58:59]
	v_bfe_u32 v30, v29, 16, 1
	v_bfe_u32 v31, v28, 16, 1
	v_bfe_u32 v38, v3, 16, 1
	v_bfe_u32 v40, v1, 16, 1
	v_add3_u32 v1, v1, v40, s34
	v_add3_u32 v3, v3, v38, s34
	v_add3_u32 v40, v28, v31, s34
	v_add3_u32 v38, v29, v30, s34
	ds_read_b128 v[28:31], v124
	v_cndmask_b32_e64 v2, 0, v45, s[44:45]
	v_cndmask_b32_e64 v32, v37, 0, s[52:53]
	v_cndmask_b32_e64 v34, v39, 0, s[56:57]
	v_bfe_u32 v35, v34, 16, 1
	v_bfe_u32 v36, v33, 16, 1
	v_bfe_u32 v37, v32, 16, 1
	v_bfe_u32 v39, v2, 16, 1
	v_add3_u32 v2, v2, v39, s34
	v_add3_u32 v37, v32, v37, s34
	v_add3_u32 v36, v33, v36, s34
	v_add3_u32 v39, v34, v35, s34
	v_perm_b32 v39, v39, v36, s35
	v_perm_b32 v38, v37, v38, s35
	v_perm_b32 v37, v40, v3, s35
	v_perm_b32 v36, v2, v1, s35
	ds_read_b128 v[32:35], v124 offset:4352
	ds_read_b128 v[44:47], v124 offset:30464
	s_waitcnt lgkmcnt(2)
	v_mfma_f32_16x16x32_bf16 v[64:67], v[28:31], v[36:39], 0
	ds_read_b128 v[28:31], v124 offset:8704
	s_waitcnt lgkmcnt(2)
	v_mfma_f32_16x16x32_bf16 v[60:63], v[32:35], v[36:39], 0
	ds_read_b128 v[32:35], v124 offset:13056
	s_waitcnt lgkmcnt(1)
	v_mfma_f32_16x16x32_bf16 v[56:59], v[28:31], v[36:39], 0
	ds_read_b128 v[28:31], v124 offset:17408
	s_waitcnt lgkmcnt(1)
	v_mfma_f32_16x16x32_bf16 v[52:55], v[32:35], v[36:39], 0
	ds_read_b128 v[32:35], v124 offset:21760
	s_waitcnt lgkmcnt(1)
	v_mfma_f32_16x16x32_bf16 v[48:51], v[28:31], v[36:39], 0
	ds_read_b128 v[28:31], v124 offset:26112
	s_waitcnt lgkmcnt(1)
	v_mfma_f32_16x16x32_bf16 v[40:43], v[32:35], v[36:39], 0
	s_waitcnt lgkmcnt(0)
	v_mfma_f32_16x16x32_bf16 v[32:35], v[28:31], v[36:39], 0
	v_mfma_f32_16x16x32_bf16 v[28:31], v[44:47], v[36:39], 0
	s_or_b64 exec, exec, s[20:21]
	s_and_saveexec_b64 s[20:21], s[60:61]
	s_cbranch_execnz .LBB0_331

.LBB0_887:
	s_or_b64 exec, exec, s[4:5]
	v_readlane_b32 s4, v254, 3
	v_readlane_b32 s5, v254, 4
	v_mov_b32_e32 v18, v213
	s_andn2_b64 vcc, exec, s[4:5]
	s_waitcnt lgkmcnt(0)
	s_barrier
	s_cbranch_vccnz .LBB0_898
	v_ashrrev_i32_e32 v1, 3, v18
	v_and_b32_e32 v2, 7, v18
	v_readlane_b32 s3, v254, 6
	v_lshlrev_b32_e32 v24, 4, v2
	v_lshl_add_u32 v22, v2, 5, 0
	v_add_u32_e32 v2, s3, v1
	v_ashrrev_i32_e32 v3, 31, v2
	v_lshlrev_b64 v[2:3], 10, v[2:3]
	v_readlane_b32 s3, v254, 8
	v_readlane_b32 s4, v253, 49
	v_readlane_b32 s5, v253, 50
	v_or_b32_e32 v2, s3, v2
	v_or_b32_e32 v2, v2, v24
	v_lshlrev_b64 v[2:3], 1, v[2:3]
	v_lshl_add_u64 v[4:5], s[4:5], 0, v[2:3]
	v_lshl_add_u64 v[6:7], s[70:71], 0, v[2:3]
	global_load_dwordx4 v[10:13], v[4:5], off offset:16
	global_load_dwordx4 v[14:17], v[4:5], off
	s_nop 0
	global_load_dwordx4 v[2:5], v[6:7], off offset:16
	s_nop 0
	global_load_dwordx4 v[6:9], v[6:7], off
	v_and_b32_e32 v20, 0x7f, v18
	v_readlane_b32 s3, v254, 52
	v_ashrrev_i32_e32 v21, 6, v18
	s_movk_i32 s20, 0x90
	v_lshl_add_u32 v37, v18, 2, s3
	v_lshl_add_u32 v38, v20, 2, s3
	s_movk_i32 s3, 0x80
	v_cmp_gt_u32_e64 s[10:11], s3, v18
	v_readlane_b32 s3, v254, 53
	v_and_b32_e32 v34, 3, v21
	v_bfe_u32 v23, v18, 4, 2
	v_mov_b32_e32 v28, s3
	v_mad_u32_u24 v35, v20, s20, v28
	v_lshlrev_b32_e32 v28, 4, v34
	s_movk_i32 s18, 0x110
	v_and_b32_e32 v19, 15, v18
	v_lshl_add_u32 v27, v1, 8, v22
	v_lshl_or_b32 v58, v23, 2, v28
	v_lshlrev_b32_e32 v30, 3, v23
	v_lshl_add_u32 v76, v23, 4, 0
	v_mad_u64_u32 v[22:23], s[12:13], v1, s18, v[22:23]
	v_ashrrev_i32_e32 v33, 2, v18
	v_or_b32_e32 v28, v28, v19
	v_add_u32_e32 v40, 0x8000, v22
	v_add_u32_e32 v41, 0x8010, v22
	v_lshlrev_b32_e32 v22, 6, v33
	v_readlane_b32 s12, v254, 11
	v_lshlrev_b32_e32 v29, 5, v34
	v_readlane_b32 s14, v254, 54
	v_mad_u32_u24 v39, v28, s18, v76
	v_ashrrev_i32_e32 v23, 31, v22
	v_readlane_b32 s13, v254, 12
	v_lshlrev_b32_e32 v28, 5, v18
	v_add3_u32 v77, s14, v29, v30
	v_lshl_add_u64 v[22:23], v[22:23], 1, s[12:13]
	v_and_b32_e32 v30, 0x60, v28
	v_mov_b32_e32 v31, v0
	v_lshl_add_u64 v[28:29], v[22:23], 0, v[30:31]
	v_mul_lo_u32 v22, v33, s20
	v_add3_u32 v42, s3, v22, v30
	v_mul_lo_u32 v22, v1, s20
	v_add3_u32 v44, s14, v22, v24
	v_lshlrev_b32_e32 v22, 6, v1
	v_readlane_b32 s12, v254, 9
	v_ashrrev_i32_e32 v23, 31, v22
	v_readlane_b32 s13, v254, 10
	v_mov_b32_e32 v25, v0
	v_ashrrev_i32_e32 v32, 7, v18
	v_lshl_add_u64 v[22:23], v[22:23], 1, s[12:13]
	v_lshl_add_u32 v26, v20, 1, 0
	v_lshl_add_u64 v[30:31], v[22:23], 0, v[24:25]
	v_add_u32_e32 v21, 8, v21
	v_lshl_or_b32 v23, v32, 4, 1
	s_movk_i32 s3, 0x880
	v_lshlrev_b32_e32 v36, 12, v32
	v_cmp_lt_i32_e64 s[4:5], 0, v32
	v_cmp_lt_i32_e64 s[6:7], 1, v32
	v_cmp_lt_i32_e64 s[8:9], 2, v32
	v_lshlrev_b32_e32 v73, 5, v32
	v_ashrrev_i32_e32 v21, 2, v21
	v_mul_lo_u32 v25, v32, s3
	v_mad_u64_u32 v[32:33], s[14:15], v23, s18, v[26:27]
	v_ashrrev_i32_e32 v18, 8, v18
	v_lshl_or_b32 v22, v21, 4, v19
	v_cmp_le_i32_e64 s[14:15], v34, v18
	v_lshl_or_b32 v18, v18, 4, v19
	v_or_b32_e32 v74, 2, v58
	v_or_b32_e32 v75, 3, v58
	v_cmp_gt_i32_e64 s[12:13], v58, v22
	v_lshlrev_b32_e32 v59, 8, v23
	v_or_b32_e32 v25, v25, v20
	v_or_b32_e32 v23, 0x200, v36
	v_or_b32_e32 v60, 0x300, v36
	v_or_b32_e32 v61, 0x400, v36
	v_or_b32_e32 v62, 0x500, v36
	v_or_b32_e32 v63, 0x600, v36
	v_or_b32_e32 v64, 0x700, v36
	v_or_b32_e32 v65, 0x800, v36
	v_or_b32_e32 v66, 0x900, v36
	v_or_b32_e32 v67, 0xa00, v36
	v_or_b32_e32 v68, 0xb00, v36
	v_or_b32_e32 v69, 0xc00, v36
	v_or_b32_e32 v70, 0xd00, v36
	v_or_b32_e32 v71, 0xe00, v36
	v_or_b32_e32 v72, 0xf00, v36
	v_mul_lo_u32 v19, v18, s18
	v_cmp_le_i32_e64 s[16:17], v34, v21
	v_mul_lo_u32 v21, v22, s18
	v_cmp_lt_i32_e64 s[18:19], v58, v22
	v_cmp_gt_i32_e64 s[42:43], v74, v22
	v_cmp_gt_i32_e64 s[44:45], v75, v22
	v_mul_lo_u32 v22, v22, s20
	v_cmp_gt_i32_e64 s[46:47], v58, v18
	v_cmp_lt_i32_e64 s[48:49], v58, v18
	v_cmp_gt_i32_e64 s[50:51], v74, v18
	v_cmp_gt_i32_e64 s[52:53], v75, v18
	v_mul_lo_u32 v18, v18, s20
	v_add_u32_e32 v43, 16, v42
	v_lshl_add_u32 v25, v25, 1, 0
	v_add_u32_e32 v33, 0x110, v32
	v_add_u32_e32 v45, 0x220, v32
	v_add_u32_e32 v46, 0x330, v32
	v_add_u32_e32 v47, 0x440, v32
	v_add_u32_e32 v48, 0x550, v32
	v_add_u32_e32 v49, 0x660, v32
	v_add_u32_e32 v50, 0x770, v32
	v_add_u32_e32 v51, 0x880, v32
	v_add_u32_e32 v52, 0x990, v32
	v_add_u32_e32 v53, 0xaa0, v32
	v_add_u32_e32 v54, 0xbb0, v32
	v_add_u32_e32 v55, 0xcc0, v32
	v_add_u32_e32 v56, 0xdd0, v32
	v_add_u32_e32 v57, 0xee0, v32
	v_lshlrev_b32_e32 v34, 2, v20
	v_add_u32_e32 v58, v26, v59
	v_add_u32_e32 v59, v26, v23
	v_add_u32_e32 v60, v26, v60
	v_add_u32_e32 v61, v26, v61
	v_add_u32_e32 v62, v26, v62
	v_add_u32_e32 v63, v26, v63
	v_add_u32_e32 v64, v26, v64
	v_add_u32_e32 v65, v26, v65
	v_add_u32_e32 v66, v26, v66
	v_add_u32_e32 v67, v26, v67
	v_add_u32_e32 v68, v26, v68
	v_add_u32_e32 v69, v26, v69
	v_add_u32_e32 v70, v26, v70
	v_add_u32_e32 v71, v26, v71
	v_add_u32_e32 v72, v26, v72
	v_add_u32_e32 v73, v35, v73
	v_add_u32_e32 v74, v76, v19
	v_add_u32_e32 v75, v77, v18
	v_add_u32_e32 v76, v76, v21
	v_add_u32_e32 v77, v77, v22
	v_readlane_b32 s3, v254, 7
	v_readlane_b32 s27, v254, 39
	v_readlane_b32 s54, v254, 38
	s_mov_b32 s28, s2
	s_waitcnt vmcnt(0)
	s_branch .LBB0_890

.LBB0_890:
	s_add_i32 s55, s28, s26
	s_cmpk_gt_i32 s55, 0x7ff
	s_cselect_b64 s[20:21], -1, 0
	s_and_b64 vcc, exec, s[20:21]
	s_waitcnt vmcnt(5)
	ds_write_b128 v27, v[6:9]
	ds_write_b128 v27, v[2:5] offset:16
	ds_write_b128 v27, v[14:17] offset:16384
	ds_write_b128 v27, v[10:13] offset:16400
	s_cbranch_vccnz .LBB0_892
	s_and_b32 s29, s54, 0xfffff800
	s_and_b32 s36, s27, 0x7c0
	s_or_b32 s29, s29, s36
	v_add_u32_e32 v2, s29, v1
	v_readlane_b32 s29, v254, 43
	v_ashrrev_i32_e32 v3, 31, v2
	s_add_i32 s29, s29, s3
	v_lshlrev_b64 v[2:3], 10, v[2:3]
	s_and_b32 s29, s29, 0x380
	v_or_b32_e32 v2, s29, v2
	v_or_b32_e32 v2, v2, v24
	v_readlane_b32 s36, v253, 49
	v_lshlrev_b64 v[10:11], 1, v[2:3]
	v_readlane_b32 s37, v253, 50
	v_lshl_add_u64 v[6:7], s[70:71], 0, v[10:11]
	global_load_dwordx4 v[2:5], v[6:7], off offset:16
	s_nop 0
	global_load_dwordx4 v[6:9], v[6:7], off
	v_lshl_add_u64 v[14:15], s[36:37], 0, v[10:11]
	global_load_dwordx4 v[10:13], v[14:15], off offset:16
	s_nop 0
	global_load_dwordx4 v[14:17], v[14:15], off

.LBB0_1179:
	s_add_i32 s92, s42, 2
	s_add_u32 s72, s36, 0x80
	s_addc_u32 s43, s37, 0
	s_add_i32 s93, 0, 0x10000
	v_add_u32_e32 v1, s93, v223
	ds_read_b128 v[50:53], v1
	ds_read_b128 v[54:57], v1 offset:1024
	ds_read_b128 v[58:61], v1 offset:2048
	ds_read_b128 v[62:65], v1 offset:3072
	s_cmp_eq_u32 s88, s42
	s_cselect_b32 s42, s66, s72
	s_cselect_b32 s43, s67, s43
	s_cselect_b32 s73, s71, s91
	s_cselect_b32 s72, s70, s27
	v_lshl_add_u64 v[178:179], s[36:37], 0, v[206:207]
	s_add_i32 m0, s79, 0xc000
	ds_read_b128 v[66:69], v230
	ds_read_b128 v[70:73], v230 offset:1024
	ds_read_b128 v[74:77], v230 offset:2048
	ds_read_b128 v[78:81], v230 offset:3072
	ds_read_b128 v[146:149], v230 offset:4096
	ds_read_b128 v[154:157], v230 offset:5120
	ds_read_b128 v[170:173], v230 offset:6144
	ds_read_b128 v[174:177], v230 offset:7168
	global_load_lds_dwordx4 v[178:179], off
	v_lshl_add_u64 v[178:179], s[36:37], 0, v[204:205]
	s_add_i32 m0, s79, 0xe000
	s_nop 0
	global_load_lds_dwordx4 v[178:179], off
	s_waitcnt lgkmcnt(8)
	s_barrier
	s_waitcnt lgkmcnt(0)
	s_setprio 1
	s_waitcnt lgkmcnt(0)
	v_mfma_f32_16x16x32_bf16 v[166:169], v[50:53], v[66:69], v[166:169]
	v_mfma_f32_16x16x32_bf16 v[162:165], v[58:61], v[66:69], v[162:165]
	v_mfma_f32_16x16x32_bf16 v[142:145], v[50:53], v[74:77], v[142:145]
	v_mfma_f32_16x16x32_bf16 v[138:141], v[58:61], v[74:77], v[138:141]
	v_mfma_f32_16x16x32_bf16 v[126:129], v[50:53], v[146:149], v[126:129]
	v_mfma_f32_16x16x32_bf16 v[122:125], v[58:61], v[146:149], v[122:125]
	v_mfma_f32_16x16x32_bf16 v[110:113], v[50:53], v[170:173], v[110:113]
	v_mfma_f32_16x16x32_bf16 v[106:109], v[58:61], v[170:173], v[106:109]
	v_mfma_f32_16x16x32_bf16 v[166:169], v[54:57], v[70:73], v[166:169]
	v_mfma_f32_16x16x32_bf16 v[162:165], v[62:65], v[70:73], v[162:165]
	v_mfma_f32_16x16x32_bf16 v[142:145], v[54:57], v[78:81], v[142:145]
	v_mfma_f32_16x16x32_bf16 v[138:141], v[62:65], v[78:81], v[138:141]
	v_mfma_f32_16x16x32_bf16 v[126:129], v[54:57], v[154:157], v[126:129]
	v_mfma_f32_16x16x32_bf16 v[122:125], v[62:65], v[154:157], v[122:125]
	v_mfma_f32_16x16x32_bf16 v[110:113], v[54:57], v[174:177], v[110:113]
	v_mfma_f32_16x16x32_bf16 v[106:109], v[62:65], v[174:177], v[106:109]
	s_setprio 0
	s_barrier
	s_add_i32 s94, 0, 0x14000
	s_add_i32 s93, s93, s78
	v_add_u32_e32 v1, s94, v223
	v_lshl_add_u64 v[214:215], s[72:73], 0, v[202:203]
	s_mov_b32 m0, s93
	ds_read_b128 v[178:181], v1
	ds_read_b128 v[182:185], v1 offset:1024
	ds_read_b128 v[186:189], v1 offset:2048
	ds_read_b128 v[190:193], v1 offset:3072
	global_load_lds_dwordx4 v[214:215], off
	v_lshl_add_u64 v[236:237], s[72:73], 0, v[200:201]
	s_add_i32 m0, s93, 0x2000
	s_nop 0
	global_load_lds_dwordx4 v[236:237], off
	s_barrier
	s_waitcnt lgkmcnt(0)
	s_setprio 1
	s_waitcnt lgkmcnt(0)
	v_mfma_f32_16x16x32_bf16 v[158:161], v[178:181], v[66:69], v[158:161]
	v_mfma_f32_16x16x32_bf16 v[66:69], v[186:189], v[66:69], v[150:153]
	v_mfma_f32_16x16x32_bf16 v[158:161], v[182:185], v[70:73], v[158:161]
	v_mfma_f32_16x16x32_bf16 v[66:69], v[190:193], v[70:73], v[66:69]
	v_mfma_f32_16x16x32_bf16 v[70:73], v[178:181], v[74:77], v[134:137]
	v_mfma_f32_16x16x32_bf16 v[74:77], v[186:189], v[74:77], v[130:133]
	v_mfma_f32_16x16x32_bf16 v[114:117], v[186:189], v[146:149], v[114:117]
	v_mfma_f32_16x16x32_bf16 v[102:105], v[178:181], v[170:173], v[102:105]
	v_mfma_f32_16x16x32_bf16 v[98:101], v[186:189], v[170:173], v[98:101]
	v_mfma_f32_16x16x32_bf16 v[70:73], v[182:185], v[78:81], v[70:73]
	v_mfma_f32_16x16x32_bf16 v[74:77], v[190:193], v[78:81], v[74:77]
	v_mfma_f32_16x16x32_bf16 v[78:81], v[178:181], v[146:149], v[118:121]
	v_mfma_f32_16x16x32_bf16 v[114:117], v[190:193], v[154:157], v[114:117]
	v_mfma_f32_16x16x32_bf16 v[102:105], v[182:185], v[174:177], v[102:105]
	v_mfma_f32_16x16x32_bf16 v[98:101], v[190:193], v[174:177], v[98:101]
	v_mfma_f32_16x16x32_bf16 v[78:81], v[182:185], v[154:157], v[78:81]
	s_setprio 0
	s_mov_b32 m0, s79
	v_lshl_add_u64 v[238:239], s[42:43], 0, v[202:203]
	s_barrier
	ds_read_b128 v[118:121], v230 offset:16384
	ds_read_b128 v[130:133], v230 offset:17408
	ds_read_b128 v[134:137], v230 offset:18432
	ds_read_b128 v[146:149], v230 offset:19456
	ds_read_b128 v[150:153], v230 offset:20480
	ds_read_b128 v[154:157], v230 offset:21504
	ds_read_b128 v[170:173], v230 offset:22528
	ds_read_b128 v[174:177], v230 offset:23552
	global_load_lds_dwordx4 v[238:239], off
	v_lshl_add_u64 v[240:241], s[42:43], 0, v[200:201]
	s_mov_b32 m0, s80
	s_nop 0
	global_load_lds_dwordx4 v[240:241], off
	s_barrier
	s_waitcnt lgkmcnt(0)
	s_setprio 1
	s_waitcnt lgkmcnt(0)
	v_mfma_f32_16x16x32_bf16 v[94:97], v[50:53], v[118:121], v[94:97]
	v_mfma_f32_16x16x32_bf16 v[90:93], v[58:61], v[118:121], v[90:93]
	v_mfma_f32_16x16x32_bf16 v[46:49], v[50:53], v[134:137], v[46:49]
	v_mfma_f32_16x16x32_bf16 v[42:45], v[58:61], v[134:137], v[42:45]
	v_mfma_f32_16x16x32_bf16 v[30:33], v[50:53], v[150:153], v[30:33]
	v_mfma_f32_16x16x32_bf16 v[26:29], v[58:61], v[150:153], v[26:29]
	v_mfma_f32_16x16x32_bf16 v[14:17], v[50:53], v[170:173], v[14:17]
	v_mfma_f32_16x16x32_bf16 v[10:13], v[58:61], v[170:173], v[10:13]
	v_mfma_f32_16x16x32_bf16 v[94:97], v[54:57], v[130:133], v[94:97]
	v_mfma_f32_16x16x32_bf16 v[90:93], v[62:65], v[130:133], v[90:93]
	v_mfma_f32_16x16x32_bf16 v[46:49], v[54:57], v[146:149], v[46:49]
	v_mfma_f32_16x16x32_bf16 v[42:45], v[62:65], v[146:149], v[42:45]
	v_mfma_f32_16x16x32_bf16 v[30:33], v[54:57], v[154:157], v[30:33]
	v_mfma_f32_16x16x32_bf16 v[26:29], v[62:65], v[154:157], v[26:29]
	v_mfma_f32_16x16x32_bf16 v[14:17], v[54:57], v[174:177], v[14:17]
	v_mfma_f32_16x16x32_bf16 v[10:13], v[62:65], v[174:177], v[10:13]
	s_setprio 0
	s_barrier
	s_add_u32 s72, s72, s4
	s_addc_u32 s73, s73, 0
	s_add_i32 s93, s94, s78
	v_lshl_add_u64 v[242:243], s[72:73], 0, v[202:203]
	s_mov_b32 m0, s93
	v_lshl_add_u64 v[244:245], s[72:73], 0, v[200:201]
	global_load_lds_dwordx4 v[242:243], off
	s_add_i32 m0, s93, 0x2000
	s_nop 0
	global_load_lds_dwordx4 v[244:245], off
	s_waitcnt vmcnt(6)
	s_barrier
	s_setprio 1
	v_mfma_f32_16x16x32_bf16 v[38:41], v[178:181], v[134:137], v[38:41]
	v_mfma_f32_16x16x32_bf16 v[34:37], v[186:189], v[134:137], v[34:37]
	v_mfma_f32_16x16x32_bf16 v[22:25], v[178:181], v[150:153], v[22:25]
	v_mfma_f32_16x16x32_bf16 v[18:21], v[186:189], v[150:153], v[18:21]
	v_mfma_f32_16x16x32_bf16 v[6:9], v[178:181], v[170:173], v[6:9]
	v_mfma_f32_16x16x32_bf16 v[2:5], v[186:189], v[170:173], v[2:5]
	v_mfma_f32_16x16x32_bf16 v[50:53], v[178:181], v[118:121], v[86:89]
	v_mfma_f32_16x16x32_bf16 v[54:57], v[186:189], v[118:121], v[82:85]
	v_mfma_f32_16x16x32_bf16 v[38:41], v[182:185], v[146:149], v[38:41]
	v_mfma_f32_16x16x32_bf16 v[34:37], v[190:193], v[146:149], v[34:37]
	v_mfma_f32_16x16x32_bf16 v[22:25], v[182:185], v[154:157], v[22:25]
	v_mfma_f32_16x16x32_bf16 v[18:21], v[190:193], v[154:157], v[18:21]
	v_mfma_f32_16x16x32_bf16 v[6:9], v[182:185], v[174:177], v[6:9]
	v_mfma_f32_16x16x32_bf16 v[2:5], v[190:193], v[174:177], v[2:5]
	v_mfma_f32_16x16x32_bf16 v[50:53], v[182:185], v[130:133], v[50:53]
	v_mfma_f32_16x16x32_bf16 v[54:57], v[190:193], v[130:133], v[54:57]
	s_setprio 0
	s_add_i32 s72, 0, 0x18000
	v_add_u32_e32 v1, s72, v223
	s_barrier
	ds_read_b128 v[58:61], v1
	ds_read_b128 v[62:65], v1 offset:1024
	ds_read_b128 v[82:85], v1 offset:2048
	ds_read_b128 v[86:89], v1 offset:3072
	s_add_u32 s42, s42, s4
	s_addc_u32 s43, s43, 0
	s_mov_b32 m0, s81
	v_lshl_add_u64 v[134:135], s[42:43], 0, v[202:203]
	ds_read_b128 v[118:121], v230 offset:32768
	ds_read_b128 v[130:133], v230 offset:33792
	ds_read_b128 v[146:149], v230 offset:34816
	ds_read_b128 v[154:157], v230 offset:35840
	ds_read_b128 v[170:173], v230 offset:36864
	ds_read_b128 v[174:177], v230 offset:37888
	ds_read_b128 v[178:181], v230 offset:38912
	ds_read_b128 v[182:185], v230 offset:39936
	global_load_lds_dwordx4 v[134:135], off
	v_lshl_add_u64 v[134:135], s[42:43], 0, v[200:201]
	s_mov_b32 m0, s82
	s_nop 0
	global_load_lds_dwordx4 v[134:135], off
	s_waitcnt lgkmcnt(8)
	s_barrier
	s_waitcnt lgkmcnt(0)
	s_setprio 1
	s_waitcnt lgkmcnt(0)
	v_mfma_f32_16x16x32_bf16 v[134:137], v[58:61], v[118:121], v[166:169]
	v_mfma_f32_16x16x32_bf16 v[166:169], v[62:65], v[130:133], v[134:137]
	v_mfma_f32_16x16x32_bf16 v[134:137], v[82:85], v[118:121], v[162:165]
	v_mfma_f32_16x16x32_bf16 v[162:165], v[86:89], v[130:133], v[134:137]
	v_mfma_f32_16x16x32_bf16 v[134:137], v[58:61], v[146:149], v[142:145]
	v_mfma_f32_16x16x32_bf16 v[142:145], v[62:65], v[154:157], v[134:137]
	v_mfma_f32_16x16x32_bf16 v[134:137], v[82:85], v[146:149], v[138:141]
	v_mfma_f32_16x16x32_bf16 v[126:129], v[58:61], v[170:173], v[126:129]
	v_mfma_f32_16x16x32_bf16 v[122:125], v[82:85], v[170:173], v[122:125]
	v_mfma_f32_16x16x32_bf16 v[110:113], v[58:61], v[178:181], v[110:113]
	v_mfma_f32_16x16x32_bf16 v[106:109], v[82:85], v[178:181], v[106:109]
	v_mfma_f32_16x16x32_bf16 v[138:141], v[86:89], v[154:157], v[134:137]
	v_mfma_f32_16x16x32_bf16 v[126:129], v[62:65], v[174:177], v[126:129]
	v_mfma_f32_16x16x32_bf16 v[122:125], v[86:89], v[174:177], v[122:125]
	v_mfma_f32_16x16x32_bf16 v[110:113], v[62:65], v[182:185], v[110:113]
	v_mfma_f32_16x16x32_bf16 v[106:109], v[86:89], v[182:185], v[106:109]
	s_setprio 0
	s_barrier
	s_add_i32 s42, 0, 0x1c000
	s_add_i32 s43, s72, s78
	v_add_u32_e32 v1, s42, v223
	v_lshl_add_u64 v[134:135], v[214:215], 0, s[22:23]
	s_mov_b32 m0, s43
	ds_read_b128 v[186:189], v1
	ds_read_b128 v[190:193], v1 offset:1024
	ds_read_b128 v[208:211], v1 offset:2048
	ds_read_b128 v[232:235], v1 offset:3072
	global_load_lds_dwordx4 v[134:135], off
	v_lshl_add_u64 v[134:135], v[236:237], 0, s[22:23]
	s_add_i32 m0, s43, 0x2000
	s_nop 0
	global_load_lds_dwordx4 v[134:135], off
	s_barrier
	s_waitcnt lgkmcnt(0)
	s_setprio 1
	s_waitcnt lgkmcnt(0)
	v_mfma_f32_16x16x32_bf16 v[66:69], v[208:211], v[118:121], v[66:69]
	v_mfma_f32_16x16x32_bf16 v[134:137], v[186:189], v[118:121], v[158:161]
	v_mfma_f32_16x16x32_bf16 v[150:153], v[232:235], v[130:133], v[66:69]
	v_mfma_f32_16x16x32_bf16 v[66:69], v[186:189], v[146:149], v[70:73]
	v_mfma_f32_16x16x32_bf16 v[158:161], v[190:193], v[130:133], v[134:137]
	v_mfma_f32_16x16x32_bf16 v[134:137], v[190:193], v[154:157], v[66:69]
	v_mfma_f32_16x16x32_bf16 v[66:69], v[208:211], v[146:149], v[74:77]
	v_mfma_f32_16x16x32_bf16 v[130:133], v[232:235], v[154:157], v[66:69]
	v_mfma_f32_16x16x32_bf16 v[66:69], v[186:189], v[170:173], v[78:81]
	v_mfma_f32_16x16x32_bf16 v[118:121], v[190:193], v[174:177], v[66:69]
	v_mfma_f32_16x16x32_bf16 v[66:69], v[208:211], v[170:173], v[114:117]
	v_mfma_f32_16x16x32_bf16 v[114:117], v[232:235], v[174:177], v[66:69]
	v_mfma_f32_16x16x32_bf16 v[66:69], v[186:189], v[178:181], v[102:105]
	v_mfma_f32_16x16x32_bf16 v[102:105], v[190:193], v[182:185], v[66:69]
	v_mfma_f32_16x16x32_bf16 v[66:69], v[208:211], v[178:181], v[98:101]
	v_mfma_f32_16x16x32_bf16 v[98:101], v[232:235], v[182:185], v[66:69]
	s_setprio 0
	s_mov_b32 m0, s86
	v_lshl_add_u64 v[178:179], v[238:239], 0, s[22:23]
	s_barrier
	s_nop 2
	ds_read_b128 v[66:69], v230 offset:49152
	ds_read_b128 v[70:73], v230 offset:50176
	ds_read_b128 v[74:77], v230 offset:51200
	ds_read_b128 v[78:81], v230 offset:52224
	ds_read_b128 v[146:149], v230 offset:53248
	ds_read_b128 v[154:157], v230 offset:54272
	ds_read_b128 v[170:173], v230 offset:55296
	ds_read_b128 v[174:177], v230 offset:56320
	global_load_lds_dwordx4 v[178:179], off
	v_lshl_add_u64 v[178:179], v[240:241], 0, s[22:23]
	s_mov_b32 m0, s87
	s_nop 0
	global_load_lds_dwordx4 v[178:179], off
	s_barrier
	s_waitcnt lgkmcnt(0)
	s_setprio 1
	s_waitcnt lgkmcnt(0)
	v_mfma_f32_16x16x32_bf16 v[94:97], v[58:61], v[66:69], v[94:97]
	v_mfma_f32_16x16x32_bf16 v[90:93], v[82:85], v[66:69], v[90:93]
	v_mfma_f32_16x16x32_bf16 v[46:49], v[58:61], v[74:77], v[46:49]
	v_mfma_f32_16x16x32_bf16 v[42:45], v[82:85], v[74:77], v[42:45]
	v_mfma_f32_16x16x32_bf16 v[30:33], v[58:61], v[146:149], v[30:33]
	v_mfma_f32_16x16x32_bf16 v[26:29], v[82:85], v[146:149], v[26:29]
	v_mfma_f32_16x16x32_bf16 v[14:17], v[58:61], v[170:173], v[14:17]
	v_mfma_f32_16x16x32_bf16 v[10:13], v[82:85], v[170:173], v[10:13]
	v_mfma_f32_16x16x32_bf16 v[94:97], v[62:65], v[70:73], v[94:97]
	v_mfma_f32_16x16x32_bf16 v[90:93], v[86:89], v[70:73], v[90:93]
	v_mfma_f32_16x16x32_bf16 v[46:49], v[62:65], v[78:81], v[46:49]
	v_mfma_f32_16x16x32_bf16 v[42:45], v[86:89], v[78:81], v[42:45]
	v_mfma_f32_16x16x32_bf16 v[30:33], v[62:65], v[154:157], v[30:33]
	v_mfma_f32_16x16x32_bf16 v[26:29], v[86:89], v[154:157], v[26:29]
	v_mfma_f32_16x16x32_bf16 v[14:17], v[62:65], v[174:177], v[14:17]
	v_mfma_f32_16x16x32_bf16 v[10:13], v[86:89], v[174:177], v[10:13]
	s_setprio 0
	s_barrier
	s_add_i32 s42, s42, s78
	v_lshl_add_u64 v[58:59], v[242:243], 0, s[22:23]
	s_mov_b32 m0, s42
	s_nop 0
	global_load_lds_dwordx4 v[58:59], off
	v_lshl_add_u64 v[58:59], v[244:245], 0, s[22:23]
	s_add_i32 m0, s42, 0x2000
	s_nop 0
	global_load_lds_dwordx4 v[58:59], off
	s_waitcnt vmcnt(6)
	s_barrier
	s_setprio 1
	v_mfma_f32_16x16x32_bf16 v[50:53], v[186:189], v[66:69], v[50:53]
	v_mfma_f32_16x16x32_bf16 v[86:89], v[190:193], v[70:73], v[50:53]
	v_mfma_f32_16x16x32_bf16 v[50:53], v[208:211], v[66:69], v[54:57]
	v_mfma_f32_16x16x32_bf16 v[38:41], v[186:189], v[74:77], v[38:41]
	v_mfma_f32_16x16x32_bf16 v[34:37], v[208:211], v[74:77], v[34:37]
	v_mfma_f32_16x16x32_bf16 v[22:25], v[186:189], v[146:149], v[22:25]
	v_mfma_f32_16x16x32_bf16 v[18:21], v[208:211], v[146:149], v[18:21]
	v_mfma_f32_16x16x32_bf16 v[6:9], v[186:189], v[170:173], v[6:9]
	v_mfma_f32_16x16x32_bf16 v[2:5], v[208:211], v[170:173], v[2:5]
	v_mfma_f32_16x16x32_bf16 v[82:85], v[232:235], v[70:73], v[50:53]
	v_mfma_f32_16x16x32_bf16 v[38:41], v[190:193], v[78:81], v[38:41]
	v_mfma_f32_16x16x32_bf16 v[34:37], v[232:235], v[78:81], v[34:37]
	v_mfma_f32_16x16x32_bf16 v[22:25], v[190:193], v[154:157], v[22:25]
	v_mfma_f32_16x16x32_bf16 v[18:21], v[232:235], v[154:157], v[18:21]
	v_mfma_f32_16x16x32_bf16 v[6:9], v[190:193], v[174:177], v[6:9]
	v_mfma_f32_16x16x32_bf16 v[2:5], v[232:235], v[174:177], v[2:5]
	s_setprio 0
	s_add_u32 s27, s27, 0x100
	s_addc_u32 s91, s91, 0
	s_add_u32 s36, s36, 0x100
	s_addc_u32 s37, s37, 0
	s_cmp_ge_u32 s92, s84
	s_mov_b32 s42, s92
	s_barrier
	s_cbranch_scc0 .LBB0_1179
	s_lshl_b32 s3, s3, 8
	s_add_i32 s27, s3, s85
	v_lshl_or_b32 v210, s38, 8, v224
	v_or_b32_e32 v146, s27, v221
	v_ashrrev_i32_e32 v147, 31, v146
	v_ashrrev_i32_e32 v211, 31, v210
	v_lshlrev_b64 v[50:51], 2, v[210:211]
	v_lshl_add_u64 v[208:209], v[210:211], 1, s[48:49]
	v_lshlrev_b64 v[148:149], 11, v[146:147]
	v_lshl_add_u64 v[52:53], s[52:53], 0, v[50:51]
	v_lshl_add_u64 v[54:55], s[54:55], 0, v[50:51]
	v_lshl_add_u64 v[148:149], v[208:209], 0, v[148:149]
	global_load_dwordx4 v[74:77], v[52:53], off
	global_load_dwordx4 v[66:69], v[52:53], off offset:16
	global_load_dwordx4 v[78:81], v[54:55], off
	global_load_dwordx4 v[70:73], v[54:55], off offset:16
	global_load_dwordx4 v[58:61], v[52:53], off offset:512
	s_nop 0
	global_load_dwordx4 v[50:53], v[52:53], off offset:528
	s_nop 0
	global_load_dwordx4 v[62:65], v[54:55], off offset:512
	s_nop 0
	global_load_dwordx4 v[54:57], v[54:55], off offset:528
	global_load_dwordx4 v[190:193], v[148:149], off
	global_load_dwordx4 v[186:189], v[148:149], off offset:256
	v_or_b32_e32 v148, 16, v146
	v_ashrrev_i32_e32 v149, 31, v148
	v_lshlrev_b64 v[148:149], 11, v[148:149]
	v_lshl_add_u64 v[148:149], v[208:209], 0, v[148:149]
	global_load_dwordx4 v[182:185], v[148:149], off
	global_load_dwordx4 v[178:181], v[148:149], off offset:256
	v_or_b32_e32 v148, 32, v146
	v_or_b32_e32 v146, 48, v146
	v_ashrrev_i32_e32 v149, 31, v148
	v_ashrrev_i32_e32 v147, 31, v146
	v_lshlrev_b64 v[148:149], 11, v[148:149]
	v_lshlrev_b64 v[146:147], 11, v[146:147]
	v_mov_b32_e32 v1, v222
	v_lshl_add_u64 v[148:149], v[208:209], 0, v[148:149]
	v_lshl_add_u64 v[146:147], v[208:209], 0, v[146:147]
	global_load_dwordx4 v[174:177], v[148:149], off
	global_load_dwordx4 v[170:173], v[148:149], off offset:256
	global_load_dwordx4 v[154:157], v[146:147], off
	s_nop 0
	global_load_dwordx4 v[146:149], v[146:147], off offset:256
	v_cndmask_b32_e64 v211, 0, 1, s[56:57]
	v_cmp_ne_u32_e64 s[42:43], 1, v211
	s_andn2_b64 vcc, exec, s[56:57]
	v_lshl_add_u32 v231, v1, 3, s33
	s_cbranch_vccnz .LBB0_1182
	ds_read_b64 v[214:215], v231
	s_waitcnt lgkmcnt(0)
	v_mov_b32_e32 v212, v215
	s_branch .LBB0_1183

.LBB0_1183:
	s_waitcnt vmcnt(0) lgkmcnt(0)
	v_lshlrev_b32_e32 v232, 16, v191
	v_and_b32_e32 v233, 0xffff0000, v191
	v_lshlrev_b32_e32 v215, 1, v210
	v_add_u32_e32 v210, s3, v1
	v_lshlrev_b32_e32 v1, 16, v190
	v_and_b32_e32 v190, 0xffff0000, v190
	v_lshlrev_b32_e32 v234, 16, v192
	v_and_b32_e32 v236, 0xffff0000, v192
	v_lshlrev_b32_e32 v238, 16, v193
	v_and_b32_e32 v240, 0xffff0000, v193
	v_sub_f32_e32 v193, v233, v214
	v_sub_f32_e32 v192, v232, v214
	v_sub_f32_e32 v191, v190, v214
	v_sub_f32_e32 v190, v1, v214
	v_pk_mul_f32 v[192:193], v[212:213], v[192:193] op_sel_hi:[0,1]
	v_pk_mul_f32 v[190:191], v[212:213], v[190:191] op_sel_hi:[0,1]
	v_pk_fma_f32 v[192:193], v[76:77], v[192:193], v[80:81]
	v_pk_fma_f32 v[190:191], v[74:75], v[190:191], v[78:79]
	v_pk_fma_f32 v[168:169], v[192:193], s[0:1], v[168:169] op_sel_hi:[1,0,1]
	v_pk_fma_f32 v[190:191], v[190:191], s[0:1], v[166:167] op_sel_hi:[1,0,1]
	v_add_f32_e32 v232, v168, v169
	v_cvt_pk_bf16_f32 v166, v190, v191
	v_cvt_pk_bf16_f32 v167, v168, v169
	v_mul_f32_e32 v237, v168, v168
	v_mul_f32_e32 v239, v169, v169
	v_sub_f32_e32 v169, v236, v214
	v_sub_f32_e32 v168, v234, v214
	v_sub_f32_e32 v241, v240, v214
	v_sub_f32_e32 v240, v238, v214
	v_pk_mul_f32 v[240:241], v[212:213], v[240:241] op_sel_hi:[0,1]
	v_pk_mul_f32 v[168:169], v[212:213], v[168:169] op_sel_hi:[0,1]
	v_pk_fma_f32 v[168:169], v[66:67], v[168:169], v[70:71]
	v_pk_fma_f32 v[240:241], v[68:69], v[240:241], v[72:73]
	v_lshl_add_u32 v211, v210, 11, v215
	v_pk_fma_f32 v[164:165], v[240:241], s[0:1], v[164:165] op_sel_hi:[1,0,1]
	v_pk_fma_f32 v[240:241], v[168:169], s[0:1], v[162:163] op_sel_hi:[1,0,1]
	v_mul_f32_e32 v162, v164, v164
	v_cvt_pk_bf16_f32 v168, v240, v241
	v_cvt_pk_bf16_f32 v169, v164, v165
	buffer_store_dwordx4 v[166:169], v211, s[28:31], 0 offen sc1
	v_pk_fma_f32 v[162:163], v[164:165], v[164:165], v[162:163] op_sel_hi:[1,1,0]
	v_lshlrev_b32_e32 v1, 16, v186
	v_lshlrev_b32_e32 v168, 16, v187
	v_and_b32_e32 v169, 0xffff0000, v187
	v_sub_f32_e32 v169, v169, v214
	v_sub_f32_e32 v168, v168, v214
	v_pk_mul_f32 v[168:169], v[212:213], v[168:169] op_sel_hi:[0,1]
	v_and_b32_e32 v162, 0xffff0000, v186
	v_lshlrev_b32_e32 v186, 16, v188
	v_and_b32_e32 v188, 0xffff0000, v188
	v_pk_fma_f32 v[168:169], v[60:61], v[168:169], v[64:65]
	v_add_f32_e32 v192, v190, v191
	v_pk_fma_f32 v[168:169], v[168:169], s[0:1], v[160:161] op_sel_hi:[1,0,1]
	v_sub_f32_e32 v161, v188, v214
	v_sub_f32_e32 v160, v186, v214
	v_pk_mul_f32 v[160:161], v[212:213], v[160:161] op_sel_hi:[0,1]
	v_pk_fma_f32 v[160:161], v[50:51], v[160:161], v[54:55]
	v_mul_f32_e32 v235, v190, v190
	v_lshlrev_b32_e32 v190, 16, v189
	v_and_b32_e32 v234, 0xffff0000, v189
	v_sub_f32_e32 v167, v162, v214
	v_sub_f32_e32 v166, v1, v214
	v_pk_fma_f32 v[246:247], v[160:161], s[0:1], v[150:151] op_sel_hi:[1,0,1]
	v_and_b32_e32 v150, 64, v216
	v_pk_mul_f32 v[166:167], v[212:213], v[166:167] op_sel_hi:[0,1]
	v_sub_f32_e32 v245, v234, v214
	v_sub_f32_e32 v244, v190, v214
	v_xor_b32_e32 v1, 16, v216
	v_add_u32_e32 v161, 64, v150
	v_mul_f32_e32 v191, v191, v191
	v_pk_fma_f32 v[166:167], v[58:59], v[166:167], v[62:63]
	v_pk_mul_f32 v[244:245], v[212:213], v[244:245] op_sel_hi:[0,1]
	v_cmp_lt_i32_e32 vcc, v1, v161
	v_mov_b32_e32 v234, v240
	v_mov_b32_e32 v190, v241
	v_mov_b32_e32 v236, v164
	v_mov_b32_e32 v238, v165
	v_mul_f32_e32 v193, v240, v240
	v_mul_f32_e32 v233, v241, v241
	v_pk_fma_f32 v[158:159], v[166:167], s[0:1], v[158:159] op_sel_hi:[1,0,1]
	v_pk_fma_f32 v[244:245], v[52:53], v[244:245], v[56:57]
	v_cndmask_b32_e32 v1, v216, v1, vcc
	v_pk_add_f32 v[190:191], v[234:235], v[190:191]
	v_pk_add_f32 v[164:165], v[236:237], v[238:239]
	v_mul_f32_e32 v167, v158, v158
	v_mul_f32_e32 v187, v159, v159
	v_mul_f32_e32 v189, v168, v168
	v_mul_f32_e32 v243, v169, v169
	v_pk_fma_f32 v[244:245], v[244:245], s[0:1], v[152:153] op_sel_hi:[1,0,1]
	v_lshlrev_b32_e32 v160, 2, v1
	v_pk_add_f32 v[164:165], v[190:191], v[164:165]
	v_pk_add_f32 v[190:191], v[192:193], v[232:233]
	v_mov_b32_e32 v1, v163
	v_mov_b32_e32 v166, v158
	v_mov_b32_e32 v186, v159
	v_mov_b32_e32 v188, v168
	v_mov_b32_e32 v242, v169
	v_cvt_pk_bf16_f32 v162, v158, v159
	v_mul_f32_e32 v151, v246, v246
	v_mul_f32_e32 v153, v247, v247
	v_mul_f32_e32 v249, v244, v244
	v_mul_f32_e32 v251, v245, v245
	v_pk_add_f32 v[190:191], v[190:191], v[0:1]
	v_pk_add_f32 v[158:159], v[166:167], v[186:187]
	v_pk_add_f32 v[166:167], v[188:189], v[242:243]
	v_mov_b32_e32 v150, v246
	v_mov_b32_e32 v152, v247
	v_mov_b32_e32 v248, v244
	v_mov_b32_e32 v250, v245
	v_pk_add_f32 v[164:165], v[164:165], v[190:191]
	v_pk_add_f32 v[158:159], v[158:159], v[166:167]
	v_pk_add_f32 v[150:151], v[150:151], v[152:153]
	v_pk_add_f32 v[152:153], v[248:249], v[250:251]
	v_pk_add_f32 v[158:159], v[158:159], v[164:165]
	v_pk_add_f32 v[150:151], v[150:151], v[152:153]
	v_xor_b32_e32 v1, 32, v216
	v_pk_add_f32 v[150:151], v[150:151], v[158:159]
	ds_bpermute_b32 v152, v160, v150
	ds_bpermute_b32 v153, v160, v151
	v_cmp_lt_i32_e32 vcc, v1, v161
	s_lshl_b32 s36, s38, 2
	s_and_b32 s72, s36, 12
	v_cndmask_b32_e32 v1, v216, v1, vcc
	v_lshlrev_b32_e32 v161, 2, v1
	s_waitcnt lgkmcnt(0)
	v_pk_add_f32 v[150:151], v[150:151], v[152:153]
	ds_bpermute_b32 v152, v161, v150
	ds_bpermute_b32 v153, v161, v151
	v_cvt_pk_bf16_f32 v163, v168, v169
	v_cvt_pk_bf16_f32 v164, v246, v247
	v_cvt_pk_bf16_f32 v165, v244, v245
	buffer_store_dwordx4 v[162:165], v211, s[28:31], 0 offen offset:256 sc1
	s_and_saveexec_b64 s[36:37], s[40:41]
	s_cbranch_execz .LBB0_1185
	v_ashrrev_i32_e32 v211, 31, v210
	v_lshlrev_b64 v[158:159], 7, v[210:211]
	v_lshl_add_u64 v[158:159], s[60:61], 0, v[158:159]
	s_lshl_b32 s38, s72, 3
	v_lshl_add_u64 v[158:159], v[158:159], 0, s[38:39]
	s_lshl_b32 s38, s83, 3
	v_lshl_add_u64 v[158:159], v[158:159], 0, s[38:39]
	s_waitcnt lgkmcnt(0)
	v_pk_add_f32 v[150:151], v[150:151], v[152:153]
	global_store_dwordx2 v[158:159], v[150:151], off

.LBB0_1188:
	v_lshlrev_b32_e32 v151, 16, v182
	v_and_b32_e32 v153, 0xffff0000, v182
	v_lshlrev_b32_e32 v159, 16, v183
	v_and_b32_e32 v164, 0xffff0000, v183
	v_sub_f32_e32 v163, v153, v158
	v_sub_f32_e32 v162, v151, v158
	v_sub_f32_e32 v165, v164, v158
	v_sub_f32_e32 v164, v159, v158
	v_pk_mul_f32 v[164:165], v[152:153], v[164:165] op_sel_hi:[0,1]
	v_pk_mul_f32 v[162:163], v[152:153], v[162:163] op_sel_hi:[0,1]
	v_pk_fma_f32 v[162:163], v[74:75], v[162:163], v[78:79]
	v_pk_fma_f32 v[164:165], v[76:77], v[164:165], v[80:81]
	v_lshlrev_b32_e32 v167, 16, v184
	v_and_b32_e32 v168, 0xffff0000, v184
	v_lshlrev_b32_e32 v182, 16, v185
	v_and_b32_e32 v183, 0xffff0000, v185
	v_pk_fma_f32 v[144:145], v[164:165], s[0:1], v[144:145] op_sel_hi:[1,0,1]
	v_pk_fma_f32 v[162:163], v[162:163], s[0:1], v[142:143] op_sel_hi:[1,0,1]
	v_add_f32_e32 v166, v144, v145
	v_cvt_pk_bf16_f32 v142, v162, v163
	v_cvt_pk_bf16_f32 v143, v144, v145
	v_add_f32_e32 v164, v162, v163
	v_mul_f32_e32 v153, v162, v162
	v_mul_f32_e32 v159, v163, v163
	v_mul_f32_e32 v163, v144, v144
	v_mul_f32_e32 v169, v145, v145
	v_sub_f32_e32 v145, v168, v158
	v_sub_f32_e32 v144, v167, v158
	v_sub_f32_e32 v183, v183, v158
	v_sub_f32_e32 v182, v182, v158
	v_pk_mul_f32 v[182:183], v[152:153], v[182:183] op_sel_hi:[0,1]
	v_pk_mul_f32 v[144:145], v[152:153], v[144:145] op_sel_hi:[0,1]
	v_add_u32_e32 v150, 16, v210
	v_pk_fma_f32 v[144:145], v[66:67], v[144:145], v[70:71]
	v_pk_fma_f32 v[182:183], v[68:69], v[182:183], v[72:73]
	v_lshl_add_u32 v1, v150, 11, v215
	v_pk_fma_f32 v[140:141], v[182:183], s[0:1], v[140:141] op_sel_hi:[1,0,1]
	v_pk_fma_f32 v[138:139], v[144:145], s[0:1], v[138:139] op_sel_hi:[1,0,1]
	v_mul_f32_e32 v162, v140, v140
	v_cvt_pk_bf16_f32 v144, v138, v139
	v_cvt_pk_bf16_f32 v145, v140, v141
	buffer_store_dwordx4 v[142:145], v1, s[28:31], 0 offen sc1
	v_pk_fma_f32 v[182:183], v[140:141], v[140:141], v[162:163] op_sel_hi:[1,1,0]
	v_lshlrev_b32_e32 v151, 16, v180
	v_lshlrev_b32_e32 v144, 16, v179
	v_and_b32_e32 v145, 0xffff0000, v179
	v_sub_f32_e32 v145, v145, v158
	v_sub_f32_e32 v144, v144, v158
	v_pk_mul_f32 v[144:145], v[152:153], v[144:145] op_sel_hi:[0,1]
	v_lshlrev_b32_e32 v142, 16, v178
	v_and_b32_e32 v143, 0xffff0000, v178
	v_and_b32_e32 v162, 0xffff0000, v180
	v_lshlrev_b32_e32 v168, 16, v181
	v_and_b32_e32 v178, 0xffff0000, v181
	v_pk_fma_f32 v[144:145], v[60:61], v[144:145], v[64:65]
	v_sub_f32_e32 v143, v143, v158
	v_sub_f32_e32 v142, v142, v158
	v_pk_fma_f32 v[144:145], v[144:145], s[0:1], v[136:137] op_sel_hi:[1,0,1]
	v_sub_f32_e32 v137, v162, v158
	v_sub_f32_e32 v136, v151, v158
	v_sub_f32_e32 v189, v178, v158
	v_sub_f32_e32 v188, v168, v158
	v_pk_mul_f32 v[142:143], v[152:153], v[142:143] op_sel_hi:[0,1]
	v_pk_mul_f32 v[188:189], v[152:153], v[188:189] op_sel_hi:[0,1]
	v_pk_mul_f32 v[136:137], v[152:153], v[136:137] op_sel_hi:[0,1]
	v_pk_fma_f32 v[142:143], v[58:59], v[142:143], v[62:63]
	v_pk_fma_f32 v[136:137], v[50:51], v[136:137], v[54:55]
	v_pk_fma_f32 v[188:189], v[52:53], v[188:189], v[56:57]
	v_pk_fma_f32 v[142:143], v[142:143], s[0:1], v[134:135] op_sel_hi:[1,0,1]
	v_pk_fma_f32 v[132:133], v[188:189], s[0:1], v[132:133] op_sel_hi:[1,0,1]
	v_cvt_pk_bf16_f32 v134, v142, v143
	v_cvt_pk_bf16_f32 v135, v144, v145
	v_pk_fma_f32 v[130:131], v[136:137], s[0:1], v[130:131] op_sel_hi:[1,0,1]
	v_mov_b32_e32 v152, v138
	v_cvt_pk_bf16_f32 v136, v130, v131
	v_cvt_pk_bf16_f32 v137, v132, v133
	v_mov_b32_e32 v158, v139
	v_mov_b32_e32 v162, v140
	v_mov_b32_e32 v168, v141
	v_mul_f32_e32 v165, v138, v138
	v_mul_f32_e32 v167, v139, v139
	buffer_store_dwordx4 v[134:137], v1, s[28:31], 0 offen offset:256 sc1
	v_mov_b32_e32 v1, v183
	v_mul_f32_e32 v179, v142, v142
	v_pk_add_f32 v[134:135], v[152:153], v[158:159]
	v_pk_add_f32 v[136:137], v[162:163], v[168:169]
	v_mul_f32_e32 v181, v143, v143
	v_pk_add_f32 v[134:135], v[134:135], v[136:137]
	v_pk_add_f32 v[136:137], v[164:165], v[166:167]
	v_mul_f32_e32 v185, v144, v144
	v_mul_f32_e32 v187, v145, v145
	v_pk_add_f32 v[136:137], v[136:137], v[0:1]
	v_mov_b32_e32 v178, v142
	v_mov_b32_e32 v180, v143
	v_mov_b32_e32 v184, v144
	v_mov_b32_e32 v186, v145
	v_mul_f32_e32 v189, v130, v130
	v_mul_f32_e32 v191, v131, v131
	v_mul_f32_e32 v193, v132, v132
	v_mul_f32_e32 v211, v133, v133
	v_pk_add_f32 v[134:135], v[134:135], v[136:137]
	v_pk_add_f32 v[136:137], v[178:179], v[180:181]
	v_pk_add_f32 v[138:139], v[184:185], v[186:187]
	v_mov_b32_e32 v188, v130
	v_mov_b32_e32 v190, v131
	v_mov_b32_e32 v192, v132
	v_mov_b32_e32 v210, v133
	v_pk_add_f32 v[136:137], v[136:137], v[138:139]
	v_pk_add_f32 v[130:131], v[188:189], v[190:191]
	v_pk_add_f32 v[132:133], v[192:193], v[210:211]
	v_pk_add_f32 v[134:135], v[136:137], v[134:135]
	v_pk_add_f32 v[130:131], v[130:131], v[132:133]
	s_nop 0
	v_pk_add_f32 v[130:131], v[130:131], v[134:135]
	ds_bpermute_b32 v132, v160, v130
	ds_bpermute_b32 v133, v160, v131
	s_waitcnt lgkmcnt(0)
	v_pk_add_f32 v[130:131], v[130:131], v[132:133]
	ds_bpermute_b32 v132, v161, v130
	ds_bpermute_b32 v133, v161, v131
	s_and_saveexec_b64 s[36:37], s[40:41]
	s_cbranch_execz .LBB0_1190
	v_ashrrev_i32_e32 v151, 31, v150
	v_lshlrev_b64 v[134:135], 7, v[150:151]
	v_lshl_add_u64 v[134:135], s[60:61], 0, v[134:135]
	s_lshl_b32 s38, s72, 3
	v_lshl_add_u64 v[134:135], v[134:135], 0, s[38:39]
	s_lshl_b32 s38, s83, 3
	v_lshl_add_u64 v[134:135], v[134:135], 0, s[38:39]
	s_waitcnt lgkmcnt(0)
	v_pk_add_f32 v[130:131], v[130:131], v[132:133]
	global_store_dwordx2 v[134:135], v[130:131], off
.LBB0_1190:
	s_or_b64 exec, exec, s[36:37]
	v_add_u32_e32 v130, s27, v225
	v_ashrrev_i32_e32 v131, 31, v130
	s_waitcnt lgkmcnt(0)
	v_lshlrev_b64 v[132:133], 11, v[130:131]
	v_or_b32_e32 v130, 16, v130
	v_ashrrev_i32_e32 v131, 31, v130
	v_lshlrev_b64 v[130:131], 11, v[130:131]
	v_mov_b32_e32 v1, v227
	v_lshl_add_u64 v[132:133], v[208:209], 0, v[132:133]
	v_lshl_add_u64 v[130:131], v[208:209], 0, v[130:131]
	global_load_dwordx4 v[142:145], v[132:133], off
	global_load_dwordx4 v[138:141], v[132:133], off offset:256
	global_load_dwordx4 v[134:137], v[130:131], off
	s_nop 0
	global_load_dwordx4 v[130:133], v[130:131], off offset:256
	s_and_b64 vcc, exec, s[42:43]
	v_lshl_add_u32 v153, v1, 3, s33
	s_cbranch_vccnz .LBB0_1192
	ds_read_b64 v[158:159], v153
	s_waitcnt lgkmcnt(0)
	v_mov_b32_e32 v152, v159
	s_branch .LBB0_1193

.LBB0_1193:
	v_lshlrev_b32_e32 v164, 16, v175
	v_and_b32_e32 v165, 0xffff0000, v175
	v_lshlrev_b32_e32 v151, 16, v174
	v_and_b32_e32 v159, 0xffff0000, v174
	v_sub_f32_e32 v165, v165, v158
	v_sub_f32_e32 v164, v164, v158
	v_sub_f32_e32 v163, v159, v158
	v_sub_f32_e32 v162, v151, v158
	v_pk_mul_f32 v[164:165], v[152:153], v[164:165] op_sel_hi:[0,1]
	v_pk_mul_f32 v[162:163], v[152:153], v[162:163] op_sel_hi:[0,1]
	v_pk_fma_f32 v[164:165], v[76:77], v[164:165], v[80:81]
	v_lshlrev_b32_e32 v167, 16, v176
	v_and_b32_e32 v168, 0xffff0000, v176
	v_lshlrev_b32_e32 v174, 16, v177
	v_and_b32_e32 v176, 0xffff0000, v177
	v_pk_fma_f32 v[162:163], v[74:75], v[162:163], v[78:79]
	v_pk_fma_f32 v[128:129], v[164:165], s[0:1], v[128:129] op_sel_hi:[1,0,1]
	v_pk_fma_f32 v[162:163], v[162:163], s[0:1], v[126:127] op_sel_hi:[1,0,1]
	v_add_f32_e32 v166, v128, v129
	v_cvt_pk_bf16_f32 v126, v162, v163
	v_cvt_pk_bf16_f32 v127, v128, v129
	v_mul_f32_e32 v169, v128, v128
	v_mul_f32_e32 v175, v129, v129
	v_sub_f32_e32 v129, v168, v158
	v_sub_f32_e32 v128, v167, v158
	v_sub_f32_e32 v177, v176, v158
	v_sub_f32_e32 v176, v174, v158
	v_pk_mul_f32 v[176:177], v[152:153], v[176:177] op_sel_hi:[0,1]
	v_pk_mul_f32 v[128:129], v[152:153], v[128:129] op_sel_hi:[0,1]
	v_add_u32_e32 v150, s3, v1
	v_pk_fma_f32 v[128:129], v[66:67], v[128:129], v[70:71]
	v_pk_fma_f32 v[176:177], v[68:69], v[176:177], v[72:73]
	v_lshl_add_u32 v1, v150, 11, v215
	v_pk_fma_f32 v[124:125], v[176:177], s[0:1], v[124:125] op_sel_hi:[1,0,1]
	v_pk_fma_f32 v[122:123], v[128:129], s[0:1], v[122:123] op_sel_hi:[1,0,1]
	v_add_f32_e32 v164, v162, v163
	v_cvt_pk_bf16_f32 v128, v122, v123
	v_cvt_pk_bf16_f32 v129, v124, v125
	buffer_store_dwordx4 v[126:129], v1, s[28:31], 0 offen sc1
	v_mul_f32_e32 v159, v162, v162
	v_mul_f32_e32 v163, v163, v163
	v_lshlrev_b32_e32 v128, 16, v171
	v_and_b32_e32 v129, 0xffff0000, v171
	v_sub_f32_e32 v129, v129, v158
	v_sub_f32_e32 v128, v128, v158
	v_mul_f32_e32 v162, v124, v124
	v_pk_mul_f32 v[128:129], v[152:153], v[128:129] op_sel_hi:[0,1]
	v_pk_fma_f32 v[176:177], v[124:125], v[124:125], v[162:163] op_sel_hi:[1,1,0]
	v_lshlrev_b32_e32 v126, 16, v170
	v_and_b32_e32 v127, 0xffff0000, v170
	v_lshlrev_b32_e32 v151, 16, v172
	v_and_b32_e32 v162, 0xffff0000, v172
	v_lshlrev_b32_e32 v168, 16, v173
	v_and_b32_e32 v170, 0xffff0000, v173
	v_pk_fma_f32 v[128:129], v[60:61], v[128:129], v[64:65]
	v_sub_f32_e32 v127, v127, v158
	v_sub_f32_e32 v126, v126, v158
	v_pk_fma_f32 v[128:129], v[128:129], s[0:1], v[120:121] op_sel_hi:[1,0,1]
	v_sub_f32_e32 v121, v162, v158
	v_sub_f32_e32 v120, v151, v158
	v_sub_f32_e32 v183, v170, v158
	v_sub_f32_e32 v182, v168, v158
	v_pk_mul_f32 v[126:127], v[152:153], v[126:127] op_sel_hi:[0,1]
	v_pk_mul_f32 v[182:183], v[152:153], v[182:183] op_sel_hi:[0,1]
	v_pk_mul_f32 v[120:121], v[152:153], v[120:121] op_sel_hi:[0,1]
	v_pk_fma_f32 v[126:127], v[58:59], v[126:127], v[62:63]
	v_pk_fma_f32 v[120:121], v[50:51], v[120:121], v[54:55]
	v_pk_fma_f32 v[182:183], v[52:53], v[182:183], v[56:57]
	v_pk_fma_f32 v[126:127], v[126:127], s[0:1], v[118:119] op_sel_hi:[1,0,1]
	v_pk_fma_f32 v[116:117], v[182:183], s[0:1], v[116:117] op_sel_hi:[1,0,1]
	v_cvt_pk_bf16_f32 v118, v126, v127
	v_cvt_pk_bf16_f32 v119, v128, v129
	v_pk_fma_f32 v[114:115], v[120:121], s[0:1], v[114:115] op_sel_hi:[1,0,1]
	v_mov_b32_e32 v158, v122
	v_cvt_pk_bf16_f32 v120, v114, v115
	v_cvt_pk_bf16_f32 v121, v116, v117
	v_mov_b32_e32 v162, v123
	v_mov_b32_e32 v168, v124
	v_mov_b32_e32 v174, v125
	v_mul_f32_e32 v165, v122, v122
	v_mul_f32_e32 v167, v123, v123
	buffer_store_dwordx4 v[118:121], v1, s[28:31], 0 offen offset:256 sc1
	v_mov_b32_e32 v1, v177
	v_mul_f32_e32 v171, v126, v126
	v_pk_add_f32 v[118:119], v[158:159], v[162:163]
	v_pk_add_f32 v[120:121], v[168:169], v[174:175]
	v_mul_f32_e32 v173, v127, v127
	v_pk_add_f32 v[118:119], v[118:119], v[120:121]
	v_pk_add_f32 v[120:121], v[164:165], v[166:167]
	v_mul_f32_e32 v179, v128, v128
	v_mul_f32_e32 v181, v129, v129
	v_pk_add_f32 v[120:121], v[120:121], v[0:1]
	v_mov_b32_e32 v170, v126
	v_mov_b32_e32 v172, v127
	v_mov_b32_e32 v178, v128
	v_mov_b32_e32 v180, v129
	v_mul_f32_e32 v183, v114, v114
	v_mul_f32_e32 v185, v115, v115
	v_mul_f32_e32 v187, v116, v116
	v_mul_f32_e32 v189, v117, v117
	v_pk_add_f32 v[118:119], v[118:119], v[120:121]
	v_pk_add_f32 v[120:121], v[170:171], v[172:173]
	v_pk_add_f32 v[122:123], v[178:179], v[180:181]
	v_mov_b32_e32 v182, v114
	v_mov_b32_e32 v184, v115
	v_mov_b32_e32 v186, v116
	v_mov_b32_e32 v188, v117
	v_pk_add_f32 v[120:121], v[120:121], v[122:123]
	v_pk_add_f32 v[114:115], v[182:183], v[184:185]
	v_pk_add_f32 v[116:117], v[186:187], v[188:189]
	v_pk_add_f32 v[118:119], v[120:121], v[118:119]
	v_pk_add_f32 v[114:115], v[114:115], v[116:117]
	s_nop 0
	v_pk_add_f32 v[114:115], v[114:115], v[118:119]
	ds_bpermute_b32 v116, v160, v114
	ds_bpermute_b32 v117, v160, v115
	s_waitcnt lgkmcnt(0)
	v_pk_add_f32 v[114:115], v[114:115], v[116:117]
	ds_bpermute_b32 v116, v161, v114
	ds_bpermute_b32 v117, v161, v115
	s_and_saveexec_b64 s[36:37], s[40:41]
	s_cbranch_execz .LBB0_1195
	v_ashrrev_i32_e32 v151, 31, v150
	v_lshlrev_b64 v[118:119], 7, v[150:151]
	v_lshl_add_u64 v[118:119], s[60:61], 0, v[118:119]
	s_lshl_b32 s38, s72, 3
	v_lshl_add_u64 v[118:119], v[118:119], 0, s[38:39]
	s_lshl_b32 s38, s83, 3
	v_lshl_add_u64 v[118:119], v[118:119], 0, s[38:39]
	s_waitcnt lgkmcnt(0)
	v_pk_add_f32 v[114:115], v[114:115], v[116:117]
	global_store_dwordx2 v[118:119], v[114:115], off

.LBB0_1198:
	v_lshlrev_b32_e32 v115, 16, v154
	v_and_b32_e32 v117, 0xffff0000, v154
	v_lshlrev_b32_e32 v119, 16, v155
	v_and_b32_e32 v122, 0xffff0000, v155
	v_sub_f32_e32 v121, v117, v118
	v_sub_f32_e32 v120, v115, v118
	v_sub_f32_e32 v123, v122, v118
	v_sub_f32_e32 v122, v119, v118
	v_pk_mul_f32 v[122:123], v[116:117], v[122:123] op_sel_hi:[0,1]
	v_pk_mul_f32 v[120:121], v[116:117], v[120:121] op_sel_hi:[0,1]
	v_pk_fma_f32 v[120:121], v[74:75], v[120:121], v[78:79]
	v_pk_fma_f32 v[122:123], v[76:77], v[122:123], v[80:81]
	v_lshlrev_b32_e32 v125, 16, v156
	v_and_b32_e32 v126, 0xffff0000, v156
	v_lshlrev_b32_e32 v128, 16, v157
	v_and_b32_e32 v129, 0xffff0000, v157
	v_pk_fma_f32 v[112:113], v[122:123], s[0:1], v[112:113] op_sel_hi:[1,0,1]
	v_pk_fma_f32 v[120:121], v[120:121], s[0:1], v[110:111] op_sel_hi:[1,0,1]
	v_add_f32_e32 v124, v112, v113
	v_cvt_pk_bf16_f32 v110, v120, v121
	v_cvt_pk_bf16_f32 v111, v112, v113
	v_add_f32_e32 v122, v120, v121
	v_mul_f32_e32 v117, v120, v120
	v_mul_f32_e32 v119, v121, v121
	v_mul_f32_e32 v121, v112, v112
	v_mul_f32_e32 v127, v113, v113
	v_sub_f32_e32 v113, v126, v118
	v_sub_f32_e32 v112, v125, v118
	v_sub_f32_e32 v129, v129, v118
	v_sub_f32_e32 v128, v128, v118
	v_pk_mul_f32 v[128:129], v[116:117], v[128:129] op_sel_hi:[0,1]
	v_pk_mul_f32 v[112:113], v[116:117], v[112:113] op_sel_hi:[0,1]
	v_add_u32_e32 v114, 16, v150
	v_pk_fma_f32 v[112:113], v[66:67], v[112:113], v[70:71]
	v_pk_fma_f32 v[128:129], v[68:69], v[128:129], v[72:73]
	v_lshl_add_u32 v1, v114, 11, v215
	v_pk_fma_f32 v[108:109], v[128:129], s[0:1], v[108:109] op_sel_hi:[1,0,1]
	v_pk_fma_f32 v[106:107], v[112:113], s[0:1], v[106:107] op_sel_hi:[1,0,1]
	v_mul_f32_e32 v120, v108, v108
	v_cvt_pk_bf16_f32 v112, v106, v107
	v_cvt_pk_bf16_f32 v113, v108, v109
	buffer_store_dwordx4 v[110:113], v1, s[28:31], 0 offen sc1
	v_pk_fma_f32 v[128:129], v[108:109], v[108:109], v[120:121] op_sel_hi:[1,1,0]
	v_lshlrev_b32_e32 v115, 16, v148
	v_lshlrev_b32_e32 v112, 16, v147
	v_and_b32_e32 v113, 0xffff0000, v147
	v_sub_f32_e32 v113, v113, v118
	v_sub_f32_e32 v112, v112, v118
	v_pk_mul_f32 v[112:113], v[116:117], v[112:113] op_sel_hi:[0,1]
	v_lshlrev_b32_e32 v110, 16, v146
	v_and_b32_e32 v111, 0xffff0000, v146
	v_and_b32_e32 v120, 0xffff0000, v148
	v_lshlrev_b32_e32 v126, 16, v149
	v_and_b32_e32 v128, 0xffff0000, v149
	v_pk_fma_f32 v[112:113], v[60:61], v[112:113], v[64:65]
	v_sub_f32_e32 v111, v111, v118
	v_sub_f32_e32 v110, v110, v118
	v_pk_fma_f32 v[112:113], v[112:113], s[0:1], v[104:105] op_sel_hi:[1,0,1]
	v_sub_f32_e32 v105, v120, v118
	v_sub_f32_e32 v104, v115, v118
	v_sub_f32_e32 v155, v128, v118
	v_sub_f32_e32 v154, v126, v118
	v_pk_mul_f32 v[110:111], v[116:117], v[110:111] op_sel_hi:[0,1]
	v_pk_mul_f32 v[154:155], v[116:117], v[154:155] op_sel_hi:[0,1]
	v_pk_mul_f32 v[104:105], v[116:117], v[104:105] op_sel_hi:[0,1]
	v_pk_fma_f32 v[110:111], v[58:59], v[110:111], v[62:63]
	v_pk_fma_f32 v[104:105], v[50:51], v[104:105], v[54:55]
	v_pk_fma_f32 v[154:155], v[52:53], v[154:155], v[56:57]
	v_pk_fma_f32 v[110:111], v[110:111], s[0:1], v[102:103] op_sel_hi:[1,0,1]
	v_pk_fma_f32 v[100:101], v[154:155], s[0:1], v[100:101] op_sel_hi:[1,0,1]
	v_cvt_pk_bf16_f32 v102, v110, v111
	v_cvt_pk_bf16_f32 v103, v112, v113
	v_pk_fma_f32 v[98:99], v[104:105], s[0:1], v[98:99] op_sel_hi:[1,0,1]
	v_mov_b32_e32 v116, v106
	v_cvt_pk_bf16_f32 v104, v98, v99
	v_cvt_pk_bf16_f32 v105, v100, v101
	v_mov_b32_e32 v118, v107
	v_mov_b32_e32 v120, v108
	v_mov_b32_e32 v126, v109
	v_mul_f32_e32 v123, v106, v106
	v_mul_f32_e32 v125, v107, v107
	buffer_store_dwordx4 v[102:105], v1, s[28:31], 0 offen offset:256 sc1
	v_mov_b32_e32 v1, v129
	v_mul_f32_e32 v147, v110, v110
	v_pk_add_f32 v[102:103], v[116:117], v[118:119]
	v_pk_add_f32 v[104:105], v[120:121], v[126:127]
	v_mul_f32_e32 v149, v111, v111
	v_pk_add_f32 v[102:103], v[102:103], v[104:105]
	v_pk_add_f32 v[104:105], v[122:123], v[124:125]
	v_mul_f32_e32 v151, v112, v112
	v_mul_f32_e32 v153, v113, v113
	v_pk_add_f32 v[104:105], v[104:105], v[0:1]
	v_mov_b32_e32 v146, v110
	v_mov_b32_e32 v148, v111
	v_mov_b32_e32 v150, v112
	v_mov_b32_e32 v152, v113
	v_mul_f32_e32 v155, v98, v98
	v_mul_f32_e32 v157, v99, v99
	v_mul_f32_e32 v159, v100, v100
	v_mul_f32_e32 v163, v101, v101
	v_pk_add_f32 v[102:103], v[102:103], v[104:105]
	v_pk_add_f32 v[104:105], v[146:147], v[148:149]
	v_pk_add_f32 v[106:107], v[150:151], v[152:153]
	v_mov_b32_e32 v154, v98
	v_mov_b32_e32 v156, v99
	v_mov_b32_e32 v158, v100
	v_mov_b32_e32 v162, v101
	v_pk_add_f32 v[104:105], v[104:105], v[106:107]
	v_pk_add_f32 v[98:99], v[154:155], v[156:157]
	v_pk_add_f32 v[100:101], v[158:159], v[162:163]
	v_pk_add_f32 v[102:103], v[104:105], v[102:103]
	v_pk_add_f32 v[98:99], v[98:99], v[100:101]
	s_nop 0
	v_pk_add_f32 v[98:99], v[98:99], v[102:103]
	ds_bpermute_b32 v100, v160, v98
	ds_bpermute_b32 v101, v160, v99
	s_waitcnt lgkmcnt(0)
	v_pk_add_f32 v[98:99], v[98:99], v[100:101]
	ds_bpermute_b32 v100, v161, v98
	ds_bpermute_b32 v101, v161, v99
	s_and_saveexec_b64 s[36:37], s[40:41]
	s_cbranch_execz .LBB0_1200
	v_ashrrev_i32_e32 v115, 31, v114
	v_lshlrev_b64 v[102:103], 7, v[114:115]
	v_lshl_add_u64 v[102:103], s[60:61], 0, v[102:103]
	s_lshl_b32 s38, s72, 3
	v_lshl_add_u64 v[102:103], v[102:103], 0, s[38:39]
	s_lshl_b32 s38, s83, 3
	v_lshl_add_u64 v[102:103], v[102:103], 0, s[38:39]
	s_waitcnt lgkmcnt(0)
	v_pk_add_f32 v[98:99], v[98:99], v[100:101]
	global_store_dwordx2 v[102:103], v[98:99], off
.LBB0_1200:
	s_or_b64 exec, exec, s[36:37]
	v_add_u32_e32 v98, s27, v226
	v_ashrrev_i32_e32 v99, 31, v98
	s_waitcnt lgkmcnt(0)
	v_lshlrev_b64 v[100:101], 11, v[98:99]
	v_or_b32_e32 v98, 16, v98
	v_ashrrev_i32_e32 v99, 31, v98
	v_lshlrev_b64 v[98:99], 11, v[98:99]
	v_mov_b32_e32 v1, v228
	v_lshl_add_u64 v[100:101], v[208:209], 0, v[100:101]
	v_lshl_add_u64 v[98:99], v[208:209], 0, v[98:99]
	global_load_dwordx4 v[110:113], v[100:101], off
	global_load_dwordx4 v[106:109], v[100:101], off offset:256
	global_load_dwordx4 v[102:105], v[98:99], off
	s_nop 0
	global_load_dwordx4 v[98:101], v[98:99], off offset:256
	s_and_b64 vcc, exec, s[42:43]
	v_lshl_add_u32 v117, v1, 3, s33
	s_cbranch_vccnz .LBB0_1202
	ds_read_b64 v[118:119], v117
	s_waitcnt lgkmcnt(0)
	v_mov_b32_e32 v116, v119
	s_branch .LBB0_1203

.LBB0_1203:
	s_waitcnt vmcnt(8)
	v_lshlrev_b32_e32 v122, 16, v143
	v_and_b32_e32 v123, 0xffff0000, v143
	v_lshlrev_b32_e32 v115, 16, v142
	v_and_b32_e32 v119, 0xffff0000, v142
	v_sub_f32_e32 v123, v123, v118
	v_sub_f32_e32 v122, v122, v118
	v_sub_f32_e32 v121, v119, v118
	v_sub_f32_e32 v120, v115, v118
	v_pk_mul_f32 v[122:123], v[116:117], v[122:123] op_sel_hi:[0,1]
	v_pk_mul_f32 v[120:121], v[116:117], v[120:121] op_sel_hi:[0,1]
	v_pk_fma_f32 v[122:123], v[76:77], v[122:123], v[80:81]
	v_lshlrev_b32_e32 v125, 16, v144
	v_and_b32_e32 v126, 0xffff0000, v144
	v_lshlrev_b32_e32 v128, 16, v145
	v_and_b32_e32 v142, 0xffff0000, v145
	v_pk_fma_f32 v[120:121], v[74:75], v[120:121], v[78:79]
	v_pk_fma_f32 v[96:97], v[122:123], s[0:1], v[96:97] op_sel_hi:[1,0,1]
	v_pk_fma_f32 v[120:121], v[120:121], s[0:1], v[94:95] op_sel_hi:[1,0,1]
	v_add_f32_e32 v124, v96, v97
	v_cvt_pk_bf16_f32 v94, v120, v121
	v_cvt_pk_bf16_f32 v95, v96, v97
	v_mul_f32_e32 v127, v96, v96
	v_mul_f32_e32 v129, v97, v97
	v_sub_f32_e32 v97, v126, v118
	v_sub_f32_e32 v96, v125, v118
	v_sub_f32_e32 v143, v142, v118
	v_sub_f32_e32 v142, v128, v118
	v_pk_mul_f32 v[142:143], v[116:117], v[142:143] op_sel_hi:[0,1]
	v_pk_mul_f32 v[96:97], v[116:117], v[96:97] op_sel_hi:[0,1]
	v_add_u32_e32 v114, s3, v1
	v_pk_fma_f32 v[96:97], v[66:67], v[96:97], v[70:71]
	v_pk_fma_f32 v[142:143], v[68:69], v[142:143], v[72:73]
	v_lshl_add_u32 v1, v114, 11, v215
	v_pk_fma_f32 v[92:93], v[142:143], s[0:1], v[92:93] op_sel_hi:[1,0,1]
	v_pk_fma_f32 v[90:91], v[96:97], s[0:1], v[90:91] op_sel_hi:[1,0,1]
	v_add_f32_e32 v122, v120, v121
	v_cvt_pk_bf16_f32 v96, v90, v91
	v_cvt_pk_bf16_f32 v97, v92, v93
	buffer_store_dwordx4 v[94:97], v1, s[28:31], 0 offen sc1
	v_mul_f32_e32 v119, v120, v120
	v_mul_f32_e32 v121, v121, v121
	v_lshlrev_b32_e32 v96, 16, v139
	v_and_b32_e32 v97, 0xffff0000, v139
	v_sub_f32_e32 v97, v97, v118
	v_sub_f32_e32 v96, v96, v118
	v_mul_f32_e32 v120, v92, v92
	v_pk_mul_f32 v[96:97], v[116:117], v[96:97] op_sel_hi:[0,1]
	v_pk_fma_f32 v[142:143], v[92:93], v[92:93], v[120:121] op_sel_hi:[1,1,0]
	v_lshlrev_b32_e32 v94, 16, v138
	v_and_b32_e32 v95, 0xffff0000, v138
	v_lshlrev_b32_e32 v115, 16, v140
	v_and_b32_e32 v120, 0xffff0000, v140
	v_lshlrev_b32_e32 v126, 16, v141
	v_and_b32_e32 v128, 0xffff0000, v141
	v_pk_fma_f32 v[96:97], v[60:61], v[96:97], v[64:65]
	v_sub_f32_e32 v95, v95, v118
	v_sub_f32_e32 v94, v94, v118
	v_pk_fma_f32 v[96:97], v[96:97], s[0:1], v[88:89] op_sel_hi:[1,0,1]
	v_sub_f32_e32 v89, v120, v118
	v_sub_f32_e32 v88, v115, v118
	v_sub_f32_e32 v149, v128, v118
	v_sub_f32_e32 v148, v126, v118
	v_pk_mul_f32 v[94:95], v[116:117], v[94:95] op_sel_hi:[0,1]
	v_pk_mul_f32 v[148:149], v[116:117], v[148:149] op_sel_hi:[0,1]
	v_pk_mul_f32 v[88:89], v[116:117], v[88:89] op_sel_hi:[0,1]
	v_pk_fma_f32 v[94:95], v[58:59], v[94:95], v[62:63]
	v_pk_fma_f32 v[88:89], v[50:51], v[88:89], v[54:55]
	v_pk_fma_f32 v[148:149], v[52:53], v[148:149], v[56:57]
	v_pk_fma_f32 v[94:95], v[94:95], s[0:1], v[86:87] op_sel_hi:[1,0,1]
	v_pk_fma_f32 v[84:85], v[148:149], s[0:1], v[84:85] op_sel_hi:[1,0,1]
	v_cvt_pk_bf16_f32 v86, v94, v95
	v_cvt_pk_bf16_f32 v87, v96, v97
	v_pk_fma_f32 v[82:83], v[88:89], s[0:1], v[82:83] op_sel_hi:[1,0,1]
	v_mov_b32_e32 v118, v90
	v_cvt_pk_bf16_f32 v88, v82, v83
	v_cvt_pk_bf16_f32 v89, v84, v85
	v_mov_b32_e32 v120, v91
	v_mov_b32_e32 v126, v92
	v_mov_b32_e32 v128, v93
	v_mul_f32_e32 v123, v90, v90
	v_mul_f32_e32 v125, v91, v91
	buffer_store_dwordx4 v[86:89], v1, s[28:31], 0 offen offset:256 sc1
	v_mov_b32_e32 v1, v143
	v_mul_f32_e32 v139, v94, v94
	v_pk_add_f32 v[86:87], v[118:119], v[120:121]
	v_pk_add_f32 v[88:89], v[126:127], v[128:129]
	v_mul_f32_e32 v141, v95, v95
	v_pk_add_f32 v[86:87], v[86:87], v[88:89]
	v_pk_add_f32 v[88:89], v[122:123], v[124:125]
	v_mul_f32_e32 v145, v96, v96
	v_mul_f32_e32 v147, v97, v97
	v_pk_add_f32 v[88:89], v[88:89], v[0:1]
	v_mov_b32_e32 v138, v94
	v_mov_b32_e32 v140, v95
	v_mov_b32_e32 v144, v96
	v_mov_b32_e32 v146, v97
	v_mul_f32_e32 v149, v82, v82
	v_mul_f32_e32 v151, v83, v83
	v_mul_f32_e32 v153, v84, v84
	v_mul_f32_e32 v155, v85, v85
	v_pk_add_f32 v[86:87], v[86:87], v[88:89]
	v_pk_add_f32 v[88:89], v[138:139], v[140:141]
	v_pk_add_f32 v[90:91], v[144:145], v[146:147]
	v_mov_b32_e32 v148, v82
	v_mov_b32_e32 v150, v83
	v_mov_b32_e32 v152, v84
	v_mov_b32_e32 v154, v85
	v_pk_add_f32 v[88:89], v[88:89], v[90:91]
	v_pk_add_f32 v[82:83], v[148:149], v[150:151]
	v_pk_add_f32 v[84:85], v[152:153], v[154:155]
	v_pk_add_f32 v[86:87], v[88:89], v[86:87]
	v_pk_add_f32 v[82:83], v[82:83], v[84:85]
	s_nop 0
	v_pk_add_f32 v[82:83], v[82:83], v[86:87]
	ds_bpermute_b32 v84, v160, v82
	ds_bpermute_b32 v85, v160, v83
	s_waitcnt lgkmcnt(0)
	v_pk_add_f32 v[82:83], v[82:83], v[84:85]
	ds_bpermute_b32 v84, v161, v82
	ds_bpermute_b32 v85, v161, v83
	s_and_saveexec_b64 s[36:37], s[40:41]
	s_cbranch_execz .LBB0_1205
	v_ashrrev_i32_e32 v115, 31, v114
	v_lshlrev_b64 v[86:87], 7, v[114:115]
	v_lshl_add_u64 v[86:87], s[60:61], 0, v[86:87]
	s_lshl_b32 s38, s72, 3
	v_lshl_add_u64 v[86:87], v[86:87], 0, s[38:39]
	s_lshl_b32 s38, s83, 3
	v_lshl_add_u64 v[86:87], v[86:87], 0, s[38:39]
	s_waitcnt lgkmcnt(0)
	v_pk_add_f32 v[82:83], v[82:83], v[84:85]
	global_store_dwordx2 v[86:87], v[82:83], off

.LBB0_1208:
	v_lshlrev_b32_e32 v83, 16, v134
	v_and_b32_e32 v85, 0xffff0000, v134
	v_lshlrev_b32_e32 v87, 16, v135
	v_and_b32_e32 v90, 0xffff0000, v135
	v_sub_f32_e32 v89, v85, v86
	v_sub_f32_e32 v88, v83, v86
	v_sub_f32_e32 v91, v90, v86
	v_sub_f32_e32 v90, v87, v86
	v_pk_mul_f32 v[90:91], v[84:85], v[90:91] op_sel_hi:[0,1]
	v_pk_mul_f32 v[88:89], v[84:85], v[88:89] op_sel_hi:[0,1]
	v_pk_fma_f32 v[88:89], v[74:75], v[88:89], v[78:79]
	v_pk_fma_f32 v[90:91], v[76:77], v[90:91], v[80:81]
	v_lshlrev_b32_e32 v93, 16, v136
	v_and_b32_e32 v94, 0xffff0000, v136
	v_lshlrev_b32_e32 v96, 16, v137
	v_and_b32_e32 v97, 0xffff0000, v137
	v_pk_fma_f32 v[48:49], v[90:91], s[0:1], v[48:49] op_sel_hi:[1,0,1]
	v_pk_fma_f32 v[88:89], v[88:89], s[0:1], v[46:47] op_sel_hi:[1,0,1]
	v_add_f32_e32 v92, v48, v49
	v_cvt_pk_bf16_f32 v46, v88, v89
	v_cvt_pk_bf16_f32 v47, v48, v49
	v_add_f32_e32 v90, v88, v89
	v_mul_f32_e32 v85, v88, v88
	v_mul_f32_e32 v87, v89, v89
	v_mul_f32_e32 v89, v48, v48
	v_mul_f32_e32 v95, v49, v49
	v_sub_f32_e32 v49, v94, v86
	v_sub_f32_e32 v48, v93, v86
	v_sub_f32_e32 v97, v97, v86
	v_sub_f32_e32 v96, v96, v86
	v_pk_mul_f32 v[96:97], v[84:85], v[96:97] op_sel_hi:[0,1]
	v_pk_mul_f32 v[48:49], v[84:85], v[48:49] op_sel_hi:[0,1]
	v_add_u32_e32 v82, 16, v114
	v_pk_fma_f32 v[48:49], v[66:67], v[48:49], v[70:71]
	v_pk_fma_f32 v[96:97], v[68:69], v[96:97], v[72:73]
	v_lshl_add_u32 v1, v82, 11, v215
	v_pk_fma_f32 v[44:45], v[96:97], s[0:1], v[44:45] op_sel_hi:[1,0,1]
	v_pk_fma_f32 v[42:43], v[48:49], s[0:1], v[42:43] op_sel_hi:[1,0,1]
	v_mul_f32_e32 v88, v44, v44
	v_cvt_pk_bf16_f32 v48, v42, v43
	v_cvt_pk_bf16_f32 v49, v44, v45
	buffer_store_dwordx4 v[46:49], v1, s[28:31], 0 offen sc1
	v_pk_fma_f32 v[96:97], v[44:45], v[44:45], v[88:89] op_sel_hi:[1,1,0]
	v_lshlrev_b32_e32 v83, 16, v132
	v_lshlrev_b32_e32 v48, 16, v131
	v_and_b32_e32 v49, 0xffff0000, v131
	v_sub_f32_e32 v49, v49, v86
	v_sub_f32_e32 v48, v48, v86
	v_pk_mul_f32 v[48:49], v[84:85], v[48:49] op_sel_hi:[0,1]
	v_lshlrev_b32_e32 v46, 16, v130
	v_and_b32_e32 v47, 0xffff0000, v130
	v_and_b32_e32 v88, 0xffff0000, v132
	v_lshlrev_b32_e32 v94, 16, v133
	v_and_b32_e32 v96, 0xffff0000, v133
	v_pk_fma_f32 v[48:49], v[60:61], v[48:49], v[64:65]
	v_sub_f32_e32 v47, v47, v86
	v_sub_f32_e32 v46, v46, v86
	v_pk_fma_f32 v[48:49], v[48:49], s[0:1], v[40:41] op_sel_hi:[1,0,1]
	v_sub_f32_e32 v41, v88, v86
	v_sub_f32_e32 v40, v83, v86
	v_sub_f32_e32 v123, v96, v86
	v_sub_f32_e32 v122, v94, v86
	v_pk_mul_f32 v[46:47], v[84:85], v[46:47] op_sel_hi:[0,1]
	v_pk_mul_f32 v[122:123], v[84:85], v[122:123] op_sel_hi:[0,1]
	v_pk_mul_f32 v[40:41], v[84:85], v[40:41] op_sel_hi:[0,1]
	v_pk_fma_f32 v[46:47], v[58:59], v[46:47], v[62:63]
	v_pk_fma_f32 v[40:41], v[50:51], v[40:41], v[54:55]
	v_pk_fma_f32 v[122:123], v[52:53], v[122:123], v[56:57]
	v_pk_fma_f32 v[46:47], v[46:47], s[0:1], v[38:39] op_sel_hi:[1,0,1]
	v_pk_fma_f32 v[36:37], v[122:123], s[0:1], v[36:37] op_sel_hi:[1,0,1]
	v_cvt_pk_bf16_f32 v38, v46, v47
	v_cvt_pk_bf16_f32 v39, v48, v49
	v_pk_fma_f32 v[34:35], v[40:41], s[0:1], v[34:35] op_sel_hi:[1,0,1]
	v_mov_b32_e32 v84, v42
	v_cvt_pk_bf16_f32 v40, v34, v35
	v_cvt_pk_bf16_f32 v41, v36, v37
	v_mov_b32_e32 v86, v43
	v_mov_b32_e32 v88, v44
	v_mov_b32_e32 v94, v45
	v_mul_f32_e32 v91, v42, v42
	v_mul_f32_e32 v93, v43, v43
	buffer_store_dwordx4 v[38:41], v1, s[28:31], 0 offen offset:256 sc1
	v_mov_b32_e32 v1, v97
	v_mul_f32_e32 v115, v46, v46
	v_pk_add_f32 v[38:39], v[84:85], v[86:87]
	v_pk_add_f32 v[40:41], v[88:89], v[94:95]
	v_mul_f32_e32 v117, v47, v47
	v_pk_add_f32 v[38:39], v[38:39], v[40:41]
	v_pk_add_f32 v[40:41], v[90:91], v[92:93]
	v_mul_f32_e32 v119, v48, v48
	v_mul_f32_e32 v121, v49, v49
	v_pk_add_f32 v[40:41], v[40:41], v[0:1]
	v_mov_b32_e32 v114, v46
	v_mov_b32_e32 v116, v47
	v_mov_b32_e32 v118, v48
	v_mov_b32_e32 v120, v49
	v_mul_f32_e32 v123, v34, v34
	v_mul_f32_e32 v125, v35, v35
	v_mul_f32_e32 v127, v36, v36
	v_mul_f32_e32 v129, v37, v37
	v_pk_add_f32 v[38:39], v[38:39], v[40:41]
	v_pk_add_f32 v[40:41], v[114:115], v[116:117]
	v_pk_add_f32 v[42:43], v[118:119], v[120:121]
	v_mov_b32_e32 v122, v34
	v_mov_b32_e32 v124, v35
	v_mov_b32_e32 v126, v36
	v_mov_b32_e32 v128, v37
	v_pk_add_f32 v[40:41], v[40:41], v[42:43]
	v_pk_add_f32 v[34:35], v[122:123], v[124:125]
	v_pk_add_f32 v[36:37], v[126:127], v[128:129]
	v_pk_add_f32 v[38:39], v[40:41], v[38:39]
	v_pk_add_f32 v[34:35], v[34:35], v[36:37]
	s_nop 0
	v_pk_add_f32 v[34:35], v[34:35], v[38:39]
	ds_bpermute_b32 v36, v160, v34
	ds_bpermute_b32 v37, v160, v35
	s_waitcnt lgkmcnt(0)
	v_pk_add_f32 v[34:35], v[34:35], v[36:37]
	ds_bpermute_b32 v36, v161, v34
	ds_bpermute_b32 v37, v161, v35
	s_and_saveexec_b64 s[36:37], s[40:41]
	s_cbranch_execz .LBB0_1210
	v_ashrrev_i32_e32 v83, 31, v82
	v_lshlrev_b64 v[38:39], 7, v[82:83]
	v_lshl_add_u64 v[38:39], s[60:61], 0, v[38:39]
	s_lshl_b32 s38, s72, 3
	v_lshl_add_u64 v[38:39], v[38:39], 0, s[38:39]
	s_lshl_b32 s38, s83, 3
	v_lshl_add_u64 v[38:39], v[38:39], 0, s[38:39]
	s_waitcnt lgkmcnt(0)
	v_pk_add_f32 v[34:35], v[34:35], v[36:37]
	global_store_dwordx2 v[38:39], v[34:35], off
.LBB0_1210:
	s_waitcnt vmcnt(4)
	s_or_b64 exec, exec, s[36:37]
	v_mov_b32_e32 v1, v229
	s_and_b64 vcc, exec, s[42:43]
	s_waitcnt lgkmcnt(0)
	v_lshl_add_u32 v37, v1, 3, s33
	s_cbranch_vccnz .LBB0_1212
	ds_read_b64 v[38:39], v37
	s_waitcnt lgkmcnt(0)
	v_mov_b32_e32 v36, v39
	s_branch .LBB0_1213

.LBB0_1213:
	v_lshlrev_b32_e32 v42, 16, v111
	v_and_b32_e32 v43, 0xffff0000, v111
	v_lshlrev_b32_e32 v35, 16, v110
	v_and_b32_e32 v39, 0xffff0000, v110
	v_sub_f32_e32 v43, v43, v38
	v_sub_f32_e32 v42, v42, v38
	v_sub_f32_e32 v41, v39, v38
	v_sub_f32_e32 v40, v35, v38
	v_pk_mul_f32 v[42:43], v[36:37], v[42:43] op_sel_hi:[0,1]
	v_pk_mul_f32 v[40:41], v[36:37], v[40:41] op_sel_hi:[0,1]
	v_pk_fma_f32 v[42:43], v[76:77], v[42:43], v[80:81]
	v_lshlrev_b32_e32 v45, 16, v112
	v_and_b32_e32 v46, 0xffff0000, v112
	v_lshlrev_b32_e32 v48, 16, v113
	v_and_b32_e32 v82, 0xffff0000, v113
	v_pk_fma_f32 v[40:41], v[74:75], v[40:41], v[78:79]
	v_pk_fma_f32 v[32:33], v[42:43], s[0:1], v[32:33] op_sel_hi:[1,0,1]
	v_pk_fma_f32 v[40:41], v[40:41], s[0:1], v[30:31] op_sel_hi:[1,0,1]
	v_add_f32_e32 v44, v32, v33
	v_cvt_pk_bf16_f32 v30, v40, v41
	v_cvt_pk_bf16_f32 v31, v32, v33
	v_mul_f32_e32 v47, v32, v32
	v_mul_f32_e32 v49, v33, v33
	v_sub_f32_e32 v33, v46, v38
	v_sub_f32_e32 v32, v45, v38
	v_sub_f32_e32 v83, v82, v38
	v_sub_f32_e32 v82, v48, v38
	v_pk_mul_f32 v[82:83], v[36:37], v[82:83] op_sel_hi:[0,1]
	v_pk_mul_f32 v[32:33], v[36:37], v[32:33] op_sel_hi:[0,1]
	v_add_u32_e32 v34, s3, v1
	v_pk_fma_f32 v[32:33], v[66:67], v[32:33], v[70:71]
	v_pk_fma_f32 v[82:83], v[68:69], v[82:83], v[72:73]
	v_lshl_add_u32 v1, v34, 11, v215
	v_pk_fma_f32 v[28:29], v[82:83], s[0:1], v[28:29] op_sel_hi:[1,0,1]
	v_pk_fma_f32 v[26:27], v[32:33], s[0:1], v[26:27] op_sel_hi:[1,0,1]
	v_add_f32_e32 v42, v40, v41
	v_cvt_pk_bf16_f32 v32, v26, v27
	v_cvt_pk_bf16_f32 v33, v28, v29
	buffer_store_dwordx4 v[30:33], v1, s[28:31], 0 offen sc1
	v_mul_f32_e32 v39, v40, v40
	v_mul_f32_e32 v41, v41, v41
	v_lshlrev_b32_e32 v32, 16, v107
	v_and_b32_e32 v33, 0xffff0000, v107
	v_sub_f32_e32 v33, v33, v38
	v_sub_f32_e32 v32, v32, v38
	v_mul_f32_e32 v40, v28, v28
	v_pk_mul_f32 v[32:33], v[36:37], v[32:33] op_sel_hi:[0,1]
	v_pk_fma_f32 v[82:83], v[28:29], v[28:29], v[40:41] op_sel_hi:[1,1,0]
	v_lshlrev_b32_e32 v30, 16, v106
	v_and_b32_e32 v31, 0xffff0000, v106
	v_lshlrev_b32_e32 v35, 16, v108
	v_and_b32_e32 v40, 0xffff0000, v108
	v_lshlrev_b32_e32 v46, 16, v109
	v_and_b32_e32 v48, 0xffff0000, v109
	v_pk_fma_f32 v[32:33], v[60:61], v[32:33], v[64:65]
	v_sub_f32_e32 v31, v31, v38
	v_sub_f32_e32 v30, v30, v38
	v_pk_fma_f32 v[32:33], v[32:33], s[0:1], v[24:25] op_sel_hi:[1,0,1]
	v_sub_f32_e32 v25, v40, v38
	v_sub_f32_e32 v24, v35, v38
	v_sub_f32_e32 v93, v48, v38
	v_sub_f32_e32 v92, v46, v38
	v_pk_mul_f32 v[30:31], v[36:37], v[30:31] op_sel_hi:[0,1]
	v_pk_mul_f32 v[92:93], v[36:37], v[92:93] op_sel_hi:[0,1]
	v_pk_mul_f32 v[24:25], v[36:37], v[24:25] op_sel_hi:[0,1]
	v_pk_fma_f32 v[30:31], v[58:59], v[30:31], v[62:63]
	v_pk_fma_f32 v[24:25], v[50:51], v[24:25], v[54:55]
	v_pk_fma_f32 v[92:93], v[52:53], v[92:93], v[56:57]
	v_pk_fma_f32 v[30:31], v[30:31], s[0:1], v[22:23] op_sel_hi:[1,0,1]
	v_pk_fma_f32 v[20:21], v[92:93], s[0:1], v[20:21] op_sel_hi:[1,0,1]
	v_cvt_pk_bf16_f32 v22, v30, v31
	v_cvt_pk_bf16_f32 v23, v32, v33
	v_pk_fma_f32 v[18:19], v[24:25], s[0:1], v[18:19] op_sel_hi:[1,0,1]
	v_mov_b32_e32 v38, v26
	v_cvt_pk_bf16_f32 v24, v18, v19
	v_cvt_pk_bf16_f32 v25, v20, v21
	v_mov_b32_e32 v40, v27
	v_mov_b32_e32 v46, v28
	v_mov_b32_e32 v48, v29
	v_mul_f32_e32 v43, v26, v26
	v_mul_f32_e32 v45, v27, v27
	buffer_store_dwordx4 v[22:25], v1, s[28:31], 0 offen offset:256 sc1
	v_mov_b32_e32 v1, v83
	v_mul_f32_e32 v85, v30, v30
	v_pk_add_f32 v[22:23], v[38:39], v[40:41]
	v_pk_add_f32 v[24:25], v[46:47], v[48:49]
	v_mul_f32_e32 v87, v31, v31
	v_pk_add_f32 v[22:23], v[22:23], v[24:25]
	v_pk_add_f32 v[24:25], v[42:43], v[44:45]
	v_mul_f32_e32 v89, v32, v32
	v_mul_f32_e32 v91, v33, v33
	v_pk_add_f32 v[24:25], v[24:25], v[0:1]
	v_mov_b32_e32 v84, v30
	v_mov_b32_e32 v86, v31
	v_mov_b32_e32 v88, v32
	v_mov_b32_e32 v90, v33
	v_mul_f32_e32 v93, v18, v18
	v_mul_f32_e32 v95, v19, v19
	v_mul_f32_e32 v97, v20, v20
	v_mul_f32_e32 v107, v21, v21
	v_pk_add_f32 v[22:23], v[22:23], v[24:25]
	v_pk_add_f32 v[24:25], v[84:85], v[86:87]
	v_pk_add_f32 v[26:27], v[88:89], v[90:91]
	v_mov_b32_e32 v92, v18
	v_mov_b32_e32 v94, v19
	v_mov_b32_e32 v96, v20
	v_mov_b32_e32 v106, v21
	v_pk_add_f32 v[24:25], v[24:25], v[26:27]
	v_pk_add_f32 v[18:19], v[92:93], v[94:95]
	v_pk_add_f32 v[20:21], v[96:97], v[106:107]
	v_pk_add_f32 v[22:23], v[24:25], v[22:23]
	v_pk_add_f32 v[18:19], v[18:19], v[20:21]
	s_nop 0
	v_pk_add_f32 v[18:19], v[18:19], v[22:23]
	ds_bpermute_b32 v20, v160, v18
	ds_bpermute_b32 v21, v160, v19
	s_waitcnt lgkmcnt(0)
	v_pk_add_f32 v[18:19], v[18:19], v[20:21]
	ds_bpermute_b32 v20, v161, v18
	ds_bpermute_b32 v21, v161, v19
	s_and_saveexec_b64 s[36:37], s[40:41]
	s_cbranch_execz .LBB0_1215
	v_ashrrev_i32_e32 v35, 31, v34
	v_lshlrev_b64 v[22:23], 7, v[34:35]
	v_lshl_add_u64 v[22:23], s[60:61], 0, v[22:23]
	s_lshl_b32 s38, s72, 3
	v_lshl_add_u64 v[22:23], v[22:23], 0, s[38:39]
	s_lshl_b32 s38, s83, 3
	v_lshl_add_u64 v[22:23], v[22:23], 0, s[38:39]
	s_waitcnt lgkmcnt(0)
	v_pk_add_f32 v[18:19], v[18:19], v[20:21]
	global_store_dwordx2 v[22:23], v[18:19], off

.LBB0_1218:
	v_lshlrev_b32_e32 v1, 16, v102
	v_and_b32_e32 v21, 0xffff0000, v102
	v_sub_f32_e32 v25, v21, v22
	v_sub_f32_e32 v24, v1, v22
	v_pk_mul_f32 v[24:25], v[20:21], v[24:25] op_sel_hi:[0,1]
	v_lshlrev_b32_e32 v23, 16, v103
	v_and_b32_e32 v26, 0xffff0000, v103
	v_pk_fma_f32 v[24:25], v[74:75], v[24:25], v[78:79]
	v_lshlrev_b32_e32 v32, 16, v105
	v_and_b32_e32 v33, 0xffff0000, v105
	v_sub_f32_e32 v27, v26, v22
	v_sub_f32_e32 v26, v23, v22
	v_pk_fma_f32 v[24:25], v[24:25], s[0:1], v[14:15] op_sel_hi:[1,0,1]
	v_pk_mul_f32 v[26:27], v[20:21], v[26:27] op_sel_hi:[0,1]
	v_mul_f32_e32 v21, v24, v24
	v_sub_f32_e32 v33, v33, v22
	v_sub_f32_e32 v32, v32, v22
	v_lshlrev_b32_e32 v29, 16, v104
	v_and_b32_e32 v30, 0xffff0000, v104
	v_pk_mul_f32 v[32:33], v[20:21], v[32:33] op_sel_hi:[0,1]
	v_pk_fma_f32 v[26:27], v[76:77], v[26:27], v[80:81]
	v_sub_f32_e32 v31, v30, v22
	v_sub_f32_e32 v30, v29, v22
	v_pk_fma_f32 v[32:33], v[68:69], v[32:33], v[72:73]
	v_pk_fma_f32 v[16:17], v[26:27], s[0:1], v[16:17] op_sel_hi:[1,0,1]
	v_pk_mul_f32 v[30:31], v[20:21], v[30:31] op_sel_hi:[0,1]
	v_pk_fma_f32 v[12:13], v[32:33], s[0:1], v[12:13] op_sel_hi:[1,0,1]
	v_cvt_pk_bf16_f32 v14, v24, v25
	v_cvt_pk_bf16_f32 v15, v16, v17
	v_add_f32_e32 v26, v24, v25
	v_add_f32_e32 v28, v16, v17
	v_mul_f32_e32 v23, v25, v25
	v_mul_f32_e32 v25, v16, v16
	v_mul_f32_e32 v17, v17, v17
	v_pk_fma_f32 v[30:31], v[66:67], v[30:31], v[70:71]
	v_mul_f32_e32 v16, v12, v12
	v_pk_fma_f32 v[10:11], v[30:31], s[0:1], v[10:11] op_sel_hi:[1,0,1]
	v_pk_fma_f32 v[30:31], v[12:13], v[12:13], v[16:17] op_sel_hi:[1,1,0]
	v_lshlrev_b32_e32 v1, 16, v98
	v_and_b32_e32 v16, 0xffff0000, v98
	v_lshlrev_b32_e32 v24, 16, v99
	v_and_b32_e32 v30, 0xffff0000, v99
	v_lshlrev_b32_e32 v36, 16, v100
	v_and_b32_e32 v38, 0xffff0000, v100
	v_lshlrev_b32_e32 v42, 16, v101
	v_and_b32_e32 v43, 0xffff0000, v101
	v_add_u32_e32 v18, 16, v34
	v_sub_f32_e32 v33, v16, v22
	v_sub_f32_e32 v32, v1, v22
	v_sub_f32_e32 v35, v30, v22
	v_sub_f32_e32 v34, v24, v22
	v_sub_f32_e32 v41, v38, v22
	v_sub_f32_e32 v40, v36, v22
	v_sub_f32_e32 v43, v43, v22
	v_sub_f32_e32 v42, v42, v22
	v_pk_mul_f32 v[34:35], v[20:21], v[34:35] op_sel_hi:[0,1]
	v_pk_mul_f32 v[32:33], v[20:21], v[32:33] op_sel_hi:[0,1]
	v_pk_mul_f32 v[42:43], v[20:21], v[42:43] op_sel_hi:[0,1]
	v_pk_mul_f32 v[40:41], v[20:21], v[40:41] op_sel_hi:[0,1]
	v_mov_b32_e32 v20, v10
	v_mov_b32_e32 v22, v11
	v_mov_b32_e32 v24, v12
	v_mov_b32_e32 v16, v13
	v_mul_f32_e32 v27, v10, v10
	v_mul_f32_e32 v29, v11, v11
	v_pk_fma_f32 v[32:33], v[58:59], v[32:33], v[62:63]
	v_pk_fma_f32 v[34:35], v[60:61], v[34:35], v[64:65]
	v_pk_add_f32 v[20:21], v[20:21], v[22:23]
	v_pk_add_f32 v[16:17], v[24:25], v[16:17]
	v_pk_fma_f32 v[8:9], v[34:35], s[0:1], v[8:9] op_sel_hi:[1,0,1]
	v_pk_fma_f32 v[6:7], v[32:33], s[0:1], v[6:7] op_sel_hi:[1,0,1]
	v_pk_fma_f32 v[40:41], v[50:51], v[40:41], v[54:55]
	v_pk_fma_f32 v[42:43], v[52:53], v[42:43], v[56:57]
	v_pk_add_f32 v[16:17], v[20:21], v[16:17]
	v_pk_add_f32 v[20:21], v[26:27], v[28:29]
	v_mov_b32_e32 v1, v31
	v_mul_f32_e32 v33, v6, v6
	v_mul_f32_e32 v35, v7, v7
	v_mul_f32_e32 v37, v8, v8
	v_mul_f32_e32 v39, v9, v9
	v_pk_fma_f32 v[42:43], v[42:43], s[0:1], v[4:5] op_sel_hi:[1,0,1]
	v_pk_fma_f32 v[40:41], v[40:41], s[0:1], v[2:3] op_sel_hi:[1,0,1]
	v_pk_add_f32 v[20:21], v[20:21], v[0:1]
	v_mov_b32_e32 v32, v6
	v_mov_b32_e32 v34, v7
	v_mov_b32_e32 v36, v8
	v_mov_b32_e32 v38, v9
	v_mul_f32_e32 v3, v40, v40
	v_mul_f32_e32 v5, v41, v41
	v_mul_f32_e32 v45, v42, v42
	v_mul_f32_e32 v47, v43, v43
	v_pk_add_f32 v[16:17], v[16:17], v[20:21]
	v_pk_add_f32 v[20:21], v[32:33], v[34:35]
	v_pk_add_f32 v[22:23], v[36:37], v[38:39]
	v_mov_b32_e32 v2, v40
	v_mov_b32_e32 v4, v41
	v_mov_b32_e32 v44, v42
	v_mov_b32_e32 v46, v43
	v_pk_add_f32 v[20:21], v[20:21], v[22:23]
	v_pk_add_f32 v[2:3], v[2:3], v[4:5]
	v_pk_add_f32 v[4:5], v[44:45], v[46:47]
	v_pk_add_f32 v[16:17], v[20:21], v[16:17]
	v_pk_add_f32 v[2:3], v[2:3], v[4:5]
	v_lshl_add_u32 v19, v18, 11, v215
	v_pk_add_f32 v[2:3], v[2:3], v[16:17]
	ds_bpermute_b32 v4, v160, v2
	ds_bpermute_b32 v5, v160, v3
	v_cvt_pk_bf16_f32 v16, v10, v11
	v_cvt_pk_bf16_f32 v17, v12, v13
	buffer_store_dwordx4 v[14:17], v19, s[28:31], 0 offen sc1
	v_cvt_pk_bf16_f32 v6, v6, v7
	s_waitcnt lgkmcnt(0)
	v_pk_add_f32 v[2:3], v[2:3], v[4:5]
	ds_bpermute_b32 v4, v161, v2
	ds_bpermute_b32 v5, v161, v3
	v_cvt_pk_bf16_f32 v7, v8, v9
	v_cvt_pk_bf16_f32 v8, v40, v41
	v_cvt_pk_bf16_f32 v9, v42, v43
	buffer_store_dwordx4 v[6:9], v19, s[28:31], 0 offen offset:256 sc1
	s_and_saveexec_b64 s[36:37], s[40:41]
	s_cbranch_execz .LBB0_1173
	v_ashrrev_i32_e32 v19, 31, v18
	v_lshlrev_b64 v[6:7], 7, v[18:19]
	v_lshl_add_u64 v[6:7], s[60:61], 0, v[6:7]
	s_lshl_b32 s38, s72, 3
	v_lshl_add_u64 v[6:7], v[6:7], 0, s[38:39]
	s_lshl_b32 s38, s83, 3
	v_lshl_add_u64 v[6:7], v[6:7], 0, s[38:39]
	s_waitcnt lgkmcnt(0)
	v_pk_add_f32 v[2:3], v[2:3], v[4:5]
	global_store_dwordx2 v[6:7], v[2:3], off
	s_branch .LBB0_1173
